# batch3: P11 token prologue loads grouped, P10 ks2 fragments prefetched, P5 PV third V-fragment buffer, P2 reduction chains interleaved
# speedup vs baseline: 1.1260x; 1.0005x over previous
; __device__ __forceinline__ unsigned pk2(float lo, float hi) { f32v2_t v = {lo, hi}; bf16v2_t r = __builtin_convertvector(v, bf16v2_t); return __builtin_bit_cast(unsigned, r); }
; __device__ void phase_small(const Params& p) {
;     ...
;   for (int t = gw; t < T; t += nw) {
;     {
;       f32x4 v = *(const f32x4*)(zcq + (size_t)t * 256 + lane * 4);
;       float ss = wave_sum(v[0] * v[0] + v[1] * v[1] + v[2] * v[2] + v[3] * v[3]);
;       const float rs = rsqrtf(ss * (1.f / 256.f) + EPS);
;       f32x4 g = *(const f32x4*)(p.in[11] + lane * 4);
;       u32x2 w; w.x = pk2(v[0] * rs * g[0], v[1] * rs * g[1]); w.y = pk2(v[2] * rs * g[2], v[3] * rs * g[3]);
;       *(u32x2*)(cq + (size_t)t * LDQ + lane * 4) = w;
;     }
;     const int kr = keyrow_of_token(t);
;     {
;       float2 v = *(const float2*)(zckv + (size_t)t * 128 + lane * 2);
;       float ss = wave_sum(v.x * v.x + v.y * v.y);
;       const float rs = rsqrtf(ss * (1.f / 128.f) + EPS);
;       float2 g = *(const float2*)(p.in[13] + lane * 2);
;       const float a = v.x * rs * g.x, b = v.y * rs * g.y;
;       float* o = (t < TP) ? p.out + O_CP + (size_t)t * 128 : p.out + O_CS + (size_t)(t - TP) * 128;
;       *(float2*)(o + lane * 2) = make_float2(a, b);
;       *(unsigned*)(ckva + (size_t)kr * LDK + lane * 2) = pk2(a, b);
.LBB0_349:
	v_lshl_add_u64 v[46:47], s[96:97], 0, v[32:33]
	global_load_dwordx4 v[64:67], v[46:47], off
	v_lshl_add_u64 v[106:107], s[96:97], 0, v[38:39]
	global_load_dwordx2 v[108:109], v[106:107], off
	s_mov_b32 s0, 0x8000
	v_cmp_gt_u32_e64 s[44:45], s0, v44
	s_mov_b64 s[0:1], exec
	s_and_b64 exec, exec, s[42:43]
	v_lshl_add_u64 v[110:111], s[96:97], 0, v[42:43]
	v_add_co_u32_e32 v110, vcc, 0x19a5e000, v110
	v_and_b32_e32 v116, 0xfff, v44
	v_and_or_b32 v117, v44, 63, v58
	v_addc_co_u32_e32 v111, vcc, 0, v111, vcc
	v_cndmask_b32_e64 v116, v117, v116, s[44:45]
	global_load_dword v112, v[110:111], off
	v_lshl_or_b32 v116, v116, 7, v49
	global_load_dword v113, v[110:111], off offset:64
	s_nop 0
	global_load_dwordx2 v[114:115], v116, s[36:37]
	s_mov_b64 exec, s[0:1]
	s_movk_i32 s0, 0x7fff
	s_waitcnt vmcnt(3)
	v_pk_mul_f32 v[68:69], v[64:65], v[64:65]
	v_pk_mul_f32 v[118:119], v[108:109], v[108:109]
	v_pk_mul_f32 v[46:47], v[66:67], v[66:67]
	v_add_f32_e32 v2, v68, v69
	v_add_f32_e32 v118, v118, v119
	v_add_f32_e32 v2, v46, v2
	v_add_f32_e32 v2, v47, v2
	ds_bpermute_b32 v25, v29, v2
	ds_bpermute_b32 v119, v29, v118
	s_waitcnt lgkmcnt(0)
	v_add_f32_e32 v2, v2, v25
	v_add_f32_e32 v118, v118, v119
	ds_bpermute_b32 v25, v31, v2
	ds_bpermute_b32 v119, v31, v118
	s_waitcnt lgkmcnt(0)
	v_add_f32_e32 v2, v2, v25
	v_add_f32_e32 v118, v118, v119
	ds_bpermute_b32 v25, v59, v2
	ds_bpermute_b32 v119, v59, v118
	s_waitcnt lgkmcnt(0)
	v_add_f32_e32 v2, v2, v25
	v_add_f32_e32 v118, v118, v119
	ds_bpermute_b32 v25, v60, v2
	ds_bpermute_b32 v119, v60, v118
	s_waitcnt lgkmcnt(0)
	v_add_f32_e32 v2, v2, v25
	v_add_f32_e32 v118, v118, v119
	ds_bpermute_b32 v25, v61, v2
	ds_bpermute_b32 v119, v61, v118
	s_waitcnt lgkmcnt(0)
	v_add_f32_e32 v2, v2, v25
	v_add_f32_e32 v118, v118, v119
	ds_bpermute_b32 v25, v62, v2
	ds_bpermute_b32 v119, v62, v118
	s_waitcnt lgkmcnt(0)
	v_add_f32_e32 v2, v2, v25
	v_add_f32_e32 v118, v118, v119
	v_fmamk_f32 v2, v2, 0x3b800000, v48
	v_cmp_gt_f32_e32 vcc, s26, v2
	v_mul_f32_e32 v25, 0x4b800000, v2
	s_nop 0
	v_cndmask_b32_e32 v2, v2, v25, vcc
	v_rsq_f32_e32 v2, v2
	s_nop 0
	v_mul_f32_e32 v25, 0x45800000, v2
	v_cndmask_b32_e32 v2, v2, v25, vcc
	v_pk_mul_f32 v[46:47], v[64:65], v[2:3] op_sel_hi:[1,0]
	v_pk_mul_f32 v[64:65], v[66:67], v[2:3] op_sel_hi:[1,0]
	v_cmp_lt_u32_e32 vcc, s0, v44
	v_add_u32_e32 v2, 0xffff8000, v44
	v_pk_mul_f32 v[46:47], v[100:101], v[46:47]
	v_pk_mul_f32 v[64:65], v[102:103], v[64:65]
	v_cvt_pk_bf16_f32 v46, v46, v47
	v_cvt_pk_bf16_f32 v47, v64, v65
	v_lshl_add_u64 v[64:65], s[96:97], 0, v[34:35]
	global_store_dwordx2 v[64:65], v[46:47], off
	s_and_saveexec_b64 s[0:1], vcc
	s_xor_b64 s[0:1], exec, s[0:1]
	v_add_u32_e32 v2, 0xffff8000, v44
	v_lshrrev_b32_e32 v2, 6, v2
	s_movk_i32 s2, 0x840
	v_mul_lo_u32 v2, v2, s2
	v_and_or_b32 v2, v44, 63, v2
	v_add_u32_e32 v25, 0xffff8000, v63
	v_add_u32_e32 v2, 0x8800, v2
	v_mov_b64_e32 v[46:47], v[2:3]
	v_mov_b32_e32 v2, v25
	s_andn2_saveexec_b64 s[0:1], s[0:1]
	v_mov_b64_e32 v[46:47], v[44:45]
	s_or_b64 exec, exec, s[0:1]
	v_lshlrev_b64 v[66:67], 9, v[2:3]
	v_lshl_add_u64 v[66:67], s[80:81], 0, v[66:67]
	v_cndmask_b32_e64 v67, v67, v37, s[44:45]
	v_cndmask_b32_e64 v66, v66, v36, s[44:45]
	v_mov_b32_e32 v25, v3
	v_lshl_add_u64 v[66:67], v[66:67], 0, v[24:25]
	s_waitcnt vmcnt(1)
	v_mov_b32_e32 v25, v118
	v_fmamk_f32 v25, v25, 0x3c000000, v48
	v_cmp_gt_f32_e32 vcc, s26, v25
	v_mul_f32_e32 v27, 0x4b800000, v25
	s_nop 0
	v_cndmask_b32_e32 v25, v25, v27, vcc
	v_rsq_f32_e32 v25, v25
	s_nop 0
	v_mul_f32_e32 v27, 0x45800000, v25
	v_cndmask_b32_e32 v68, v25, v27, vcc
	v_pk_mul_f32 v[64:65], v[108:109], v[68:69] op_sel_hi:[1,0]
	v_pk_mul_f32 v[64:65], v[104:105], v[64:65]
	global_store_dwordx2 v[66:67], v[64:65], off
	v_cvt_pk_bf16_f32 v25, v64, v65
	v_mad_u64_u32 v[64:65], s[0:1], v46, s86, v[4:5]
	v_mov_b32_e32 v66, v65
	v_mad_u64_u32 v[66:67], s[0:1], v47, s86, v[66:67]
	v_mov_b32_e32 v65, v66
	global_store_dword v[64:65], v25, off
	s_and_saveexec_b64 s[0:1], s[42:43]
	s_cbranch_execz .LBB0_348
	v_lshlrev_b64 v[46:47], 6, v[46:47]
	v_lshl_add_u64 v[46:47], v[6:7], 0, v[46:47]
	v_pk_mul_f32 v[68:69], v[112:113], v[114:115]
	s_nop 0
	v_sub_f32_e32 v25, v68, v69
	v_mov_b32_e32 v68, v113
	v_mov_b32_e32 v69, v112
	v_pk_mul_f32 v[64:65], v[68:69], v[114:115]
	s_nop 0
	v_add_f32_e32 v27, v64, v65
	v_lshlrev_b64 v[64:65], 7, v[2:3]
	v_lshl_add_u64 v[64:65], s[24:25], 0, v[64:65]
	v_cndmask_b32_e64 v25, v27, v25, s[40:41]
	v_cndmask_b32_e64 v65, v65, v41, s[44:45]
	v_cndmask_b32_e64 v64, v64, v40, s[44:45]
	v_mov_b32_e32 v27, v3
	v_lshl_add_u64 v[64:65], v[64:65], 0, v[26:27]
	v_cvt_pk_bf16_f32 v2, v25, s0
	global_store_dword v[64:65], v25, off
	global_store_short v[46:47], v2, off
	s_branch .LBB0_348

; __device__ __forceinline__ unsigned pk2(float lo, float hi) { f32v2_t v = {lo, hi}; bf16v2_t r = __builtin_convertvector(v, bf16v2_t); return __builtin_bit_cast(unsigned, r); }
; __device__ __forceinline__ f32x16 mfma32(bf16x8 a, bf16x8 b, f32x16 c) { return __builtin_amdgcn_mfma_f32_32x32x16_bf16(a, b, c, 0, 0, 0); }
; __device__ void attn_item_mla(const Params& p, char* lds, int grp, int b, int h, int qblk, int dry) {
;     ...
;           f32v2_t ps2 = {0.f, 0.f}; const f32v2_t m2 = {m[qs], m[qs]};
; #pragma unroll
;           for (int r = 0; r < 16; r += 2) {
;             f32v2_t v = (f32v2_t){S[qs][r], S[qs][r + 1]} - m2;
;             v[0] = __builtin_amdgcn_exp2f(v[0]); v[1] = __builtin_amdgcn_exp2f(v[1]);
;             S[qs][r] = v[0]; S[qs][r + 1] = v[1]; ps2 += v;
;           }
;           l[qs] += ps2[0] + ps2[1];
;         }
; #pragma unroll
;         for (int s2 = 0; s2 < 2; ++s2) {
;           u32x4 w0, w1;
;           w0.x = pk2(S[0][8 * s2 + 0], S[0][8 * s2 + 1]); w0.y = pk2(S[0][8 * s2 + 2], S[0][8 * s2 + 3]);
;           w0.z = pk2(S[0][8 * s2 + 4], S[0][8 * s2 + 5]); w0.w = pk2(S[0][8 * s2 + 6], S[0][8 * s2 + 7]);
;           w1.x = pk2(S[1][8 * s2 + 0], S[1][8 * s2 + 1]); w1.y = pk2(S[1][8 * s2 + 2], S[1][8 * s2 + 3]);
;           w1.z = pk2(S[1][8 * s2 + 4], S[1][8 * s2 + 5]); w1.w = pk2(S[1][8 * s2 + 6], S[1][8 * s2 + 7]);
;           const bf16x8 pf0 = __builtin_bit_cast(bf16x8, w0), pf1 = __builtin_bit_cast(bf16x8, w1);
; #pragma unroll
;           for (int blk = 0; blk < 2; ++blk) {
;             const bf16x8 vf = *(const bf16x8*)(vp0 + blk * 32 * 144 + sub * 64 + s2 * 32);
;             O[0][blk] = mfma32(vf, pf0, O[0][blk]);
;             O[1][blk] = mfma32(vf, pf1, O[1][blk]);
;           }
;         }
.LBB0_707:
	v_sub_f32_e32 v2, v96, v0
	v_sub_f32_e32 v3, v97, v0
	v_sub_f32_e32 v4, v98, v0
	v_sub_f32_e32 v5, v99, v0
	v_exp_f32_e32 v10, v2
	v_exp_f32_e32 v11, v3
	v_exp_f32_e32 v12, v4
	v_exp_f32_e32 v13, v5
	v_sub_f32_e32 v4, v100, v0
	v_sub_f32_e32 v5, v101, v0
	v_add_f32_e32 v2, 0, v10
	v_add_f32_e32 v3, 0, v11
	v_exp_f32_e32 v96, v4
	v_exp_f32_e32 v97, v5
	v_sub_f32_e32 v4, v102, v0
	v_sub_f32_e32 v5, v103, v0
	v_add_f32_e32 v2, v12, v2
	v_add_f32_e32 v3, v13, v3
	v_exp_f32_e32 v98, v4
	v_exp_f32_e32 v99, v5
	v_add_f32_e32 v2, v96, v2
	v_add_f32_e32 v3, v97, v3
	v_sub_f32_e32 v80, v80, v220
	v_sub_f32_e32 v81, v81, v220
	v_sub_f32_e32 v82, v82, v220
	v_sub_f32_e32 v83, v83, v220
	v_add_f32_e32 v4, v98, v2
	v_add_f32_e32 v5, v99, v3
	v_sub_f32_e32 v2, v104, v0
	v_sub_f32_e32 v3, v105, v0
	v_exp_f32_e32 v80, v80
	v_exp_f32_e32 v2, v2
	v_exp_f32_e32 v3, v3
	v_exp_f32_e32 v81, v81
	v_exp_f32_e32 v82, v82
	v_exp_f32_e32 v83, v83
	v_add_f32_e32 v6, v2, v4
	v_add_f32_e32 v7, v3, v5
	v_sub_f32_e32 v4, v106, v0
	v_sub_f32_e32 v5, v107, v0
	v_sub_f32_e32 v84, v84, v220
	v_sub_f32_e32 v85, v85, v220
	v_exp_f32_e32 v4, v4
	v_exp_f32_e32 v5, v5
	v_exp_f32_e32 v84, v84
	v_exp_f32_e32 v85, v85
	v_sub_f32_e32 v86, v86, v220
	v_sub_f32_e32 v87, v87, v220
	v_add_f32_e32 v8, v4, v6
	v_add_f32_e32 v9, v5, v7
	v_sub_f32_e32 v6, v108, v0
	v_sub_f32_e32 v7, v109, v0
	v_exp_f32_e32 v86, v86
	v_exp_f32_e32 v6, v6
	v_exp_f32_e32 v7, v7
	v_exp_f32_e32 v87, v87
	v_sub_f32_e32 v88, v88, v220
	v_sub_f32_e32 v89, v89, v220
	v_sub_f32_e32 v90, v90, v220
	v_sub_f32_e32 v91, v91, v220
	v_add_f32_e32 v100, v6, v8
	v_add_f32_e32 v101, v7, v9
	v_sub_f32_e32 v8, v110, v0
	v_sub_f32_e32 v9, v111, v0
	v_exp_f32_e32 v102, v88
	v_exp_f32_e32 v8, v8
	v_exp_f32_e32 v9, v9
	v_exp_f32_e32 v103, v89
	v_lshl_add_u32 v104, s16, 6, v243
	v_cvt_pk_bf16_f32 v10, v10, v11
	v_add_f32_e32 v100, v8, v100
	v_add_f32_e32 v101, v9, v101
	v_cvt_pk_bf16_f32 v11, v12, v13
	v_add_f32_e32 v100, v100, v101
	v_add_f32_e32 v14, v14, v100
	v_add_f32_e32 v100, 0, v80
	v_add_f32_e32 v101, 0, v81
	v_cvt_pk_bf16_f32 v80, v80, v81
	v_add_f32_e32 v100, v82, v100
	v_add_f32_e32 v101, v83, v101
	v_cvt_pk_bf16_f32 v81, v82, v83
	v_add_f32_e32 v100, v84, v100
	v_add_f32_e32 v101, v85, v101
	v_cvt_pk_bf16_f32 v82, v84, v85
	v_add_f32_e32 v100, v86, v100
	v_add_f32_e32 v101, v87, v101
	v_cvt_pk_bf16_f32 v83, v86, v87
	v_add_f32_e32 v88, v102, v100
	v_add_f32_e32 v89, v103, v101
	v_exp_f32_e32 v100, v90
	v_exp_f32_e32 v101, v91
	v_sub_f32_e32 v90, v92, v220
	v_sub_f32_e32 v91, v93, v220
	v_cvt_pk_bf16_f32 v12, v96, v97
	v_exp_f32_e32 v92, v90
	v_exp_f32_e32 v93, v91
	v_sub_f32_e32 v90, v94, v220
	v_sub_f32_e32 v91, v95, v220
	v_add_f32_e32 v88, v100, v88
	v_add_f32_e32 v89, v101, v89
	v_exp_f32_e32 v94, v90
	v_exp_f32_e32 v95, v91
	v_add_f32_e32 v88, v92, v88
	v_add_f32_e32 v89, v93, v89
	v_cvt_pk_bf16_f32 v13, v98, v99
	v_cvt_pk_bf16_f32 v2, v2, v3
	v_add_f32_e32 v88, v94, v88
	v_add_f32_e32 v89, v95, v89
	v_cvt_pk_bf16_f32 v3, v4, v5
	v_add_f32_e32 v88, v88, v89
	v_add_f32_e32 v195, v195, v88
	ds_read_b128 v[84:87], v104 offset:13312
	ds_read_b128 v[88:91], v104 offset:13344
	ds_read_b128 v[108:111], v104 offset:17920
	s_waitcnt lgkmcnt(2)
	v_mfma_f32_32x32x16_bf16 v[64:79], v[84:87], v[10:13], v[64:79]
	v_cvt_pk_bf16_f32 v4, v6, v7
	v_cvt_pk_bf16_f32 v5, v8, v9
	v_cvt_pk_bf16_f32 v6, v102, v103
	v_cvt_pk_bf16_f32 v7, v100, v101
	v_cvt_pk_bf16_f32 v8, v92, v93
	v_cvt_pk_bf16_f32 v9, v94, v95
	s_xor_b64 s[0:1], s[2:3], -1
	v_mfma_f32_32x32x16_bf16 v[32:47], v[84:87], v[80:83], v[32:47]
	ds_read_b128 v[84:87], v104 offset:17952
	s_mov_b32 s16, 1
	s_mov_b64 s[2:3], 0
	s_andn2_b64 vcc, exec, s[0:1]
	s_waitcnt lgkmcnt(1)
	v_mfma_f32_32x32x16_bf16 v[48:63], v[108:111], v[10:13], v[48:63]
	v_mfma_f32_32x32x16_bf16 v[16:31], v[108:111], v[80:83], v[16:31]
	v_mfma_f32_32x32x16_bf16 v[64:79], v[88:91], v[2:5], v[64:79]
	v_mfma_f32_32x32x16_bf16 v[32:47], v[88:91], v[6:9], v[32:47]
	s_waitcnt lgkmcnt(0)
	v_mfma_f32_32x32x16_bf16 v[48:63], v[84:87], v[2:5], v[48:63]
	v_mfma_f32_32x32x16_bf16 v[16:31], v[84:87], v[6:9], v[16:31]
	s_cbranch_vccz .LBB0_712

; __device__ __forceinline__ f32x16 mfma32(bf16x8 a, bf16x8 b, f32x16 c) { return __builtin_amdgcn_mfma_f32_32x32x16_bf16(a, b, c, 0, 0, 0); }
; __device__ __forceinline__ int accrow(int reg, int hh) { return (reg & 3) + 8 * (reg >> 2) + 4 * hh; }
; __device__ void phase_peer_select(const Params& p, char* lds) {
;     ...
;       const int c = wid >> 1;
;       f32x16 acc[2][2]; zero_acc(acc);
;       const bf16_t* ap = pq + (size_t)(t0 + l31) * LDH + h * 128 + c * 64 + hh * 8;
;       const bf16_t* bp = keys + ((size_t)((h * 2 + c) * 128 + (wid & 1) * 64 + l31)) * 64 + hh * 8;
; #pragma unroll
;       for (int ks = 0; ks < 4; ++ks) {
;         bf16x8 a0 = *(const bf16x8*)(ap + ks * 16), a1 = *(const bf16x8*)(ap + 32 * LDH + ks * 16);
;         bf16x8 b0 = *(const bf16x8*)(bp + ks * 16), b1 = *(const bf16x8*)(bp + 32 * 64 + ks * 16);
;         acc[0][0] = mfma32(a0, b0, acc[0][0]); acc[0][1] = mfma32(a0, b1, acc[0][1]);
;         acc[1][0] = mfma32(a1, b0, acc[1][0]); acc[1][1] = mfma32(a1, b1, acc[1][1]);
;       }
; #pragma unroll
;       for (int i = 0; i < 2; ++i)
; #pragma unroll
;         for (int j = 0; j < 2; ++j)
; #pragma unroll
;           for (int r = 0; r < 16; ++r) S[(i * 32 + accrow(r, hh)) * 260 + c * 128 + (wid & 1) * 64 + j * 32 + l31] = acc[i][j][r];
.LBB0_1094:
	s_and_b32 s41, s3, 0xffffffc0
	s_and_b32 s37, s36, 7
	v_or_b32_e32 v2, s41, v189
	v_mov_b64_e32 v[0:1], s[84:85]
	s_movk_i32 s0, 0x880
	v_mad_i64_i32 v[0:1], s[0:1], v2, s0, v[0:1]
	s_lshl_b32 s34, s37, 8
	v_lshl_add_u64 v[0:1], v[0:1], 0, s[34:35]
	v_lshl_add_u64 v[0:1], v[0:1], 0, v[182:183]
	v_mov_b32_e32 v67, v183
	s_lshl_b32 s0, s37, 14
	v_lshl_add_u64 v[178:179], v[0:1], 0, v[66:67]
	v_add_lshl_u32 v0, s0, v76, 1
	v_mov_b32_e32 v1, v183
	s_mov_b32 s0, 0x11000
	v_lshl_add_u64 v[186:187], v[64:65], 0, v[0:1]
	global_load_dwordx4 v[0:3], v[178:179], off
	v_add_co_u32_e32 v202, vcc, s0, v178
	s_movk_i32 s0, 0x1000
	s_nop 0
	v_addc_co_u32_e32 v203, vcc, 0, v179, vcc
	v_add_co_u32_e32 v204, vcc, s0, v186
	global_load_dwordx4 v[16:19], v[202:203], off
	global_load_dwordx4 v[4:7], v[186:187], off
	v_addc_co_u32_e32 v205, vcc, 0, v187, vcc
	global_load_dwordx4 v[20:23], v[204:205], off
	global_load_dwordx4 v[174:177], v[178:179], off offset:32
	global_load_dwordx4 v[190:193], v[202:203], off offset:32
	global_load_dwordx4 v[194:197], v[186:187], off offset:32
	global_load_dwordx4 v[198:201], v[204:205], off offset:32
	global_load_dwordx4 v[208:211], v[178:179], off offset:64
	global_load_dwordx4 v[212:215], v[202:203], off offset:64
	global_load_dwordx4 v[216:219], v[186:187], off offset:64
	global_load_dwordx4 v[232:235], v[204:205], off offset:64
	s_waitcnt vmcnt(9)
	v_mfma_f32_32x32x16_bf16 v[32:47], v[0:3], v[4:7], 0
	s_waitcnt vmcnt(8)
	v_mfma_f32_32x32x16_bf16 v[48:63], v[0:3], v[20:23], 0
	v_mfma_f32_32x32x16_bf16 v[0:15], v[16:19], v[4:7], 0
	v_mfma_f32_32x32x16_bf16 v[16:31], v[16:19], v[20:23], 0
	s_waitcnt vmcnt(5)
	v_mfma_f32_32x32x16_bf16 v[32:47], v[174:177], v[194:197], v[32:47]
	s_waitcnt vmcnt(4)
	v_mfma_f32_32x32x16_bf16 v[48:63], v[174:177], v[198:201], v[48:63]
	v_mfma_f32_32x32x16_bf16 v[0:15], v[190:193], v[194:197], v[0:15]
	v_mfma_f32_32x32x16_bf16 v[16:31], v[190:193], v[198:201], v[16:31]
	global_load_dwordx4 v[174:177], v[178:179], off offset:96
	global_load_dwordx4 v[190:193], v[202:203], off offset:96
	global_load_dwordx4 v[194:197], v[186:187], off offset:96
	global_load_dwordx4 v[198:201], v[204:205], off offset:96
	s_waitcnt vmcnt(5)
	v_mfma_f32_32x32x16_bf16 v[32:47], v[208:211], v[216:219], v[32:47]
	s_waitcnt vmcnt(4)
	v_mfma_f32_32x32x16_bf16 v[48:63], v[208:211], v[232:235], v[48:63]
	v_mfma_f32_32x32x16_bf16 v[0:15], v[212:215], v[216:219], v[0:15]
	v_mfma_f32_32x32x16_bf16 v[16:31], v[212:215], v[232:235], v[16:31]
	s_waitcnt vmcnt(1)
	v_mfma_f32_32x32x16_bf16 v[32:47], v[174:177], v[194:197], v[32:47]
	s_waitcnt vmcnt(0)
	v_mfma_f32_32x32x16_bf16 v[48:63], v[174:177], v[198:201], v[48:63]
	v_mfma_f32_32x32x16_bf16 v[0:15], v[190:193], v[194:197], v[0:15]
	v_mfma_f32_32x32x16_bf16 v[16:31], v[190:193], v[198:201], v[16:31]
	s_nop 9
	ds_write2_b32 v77, v32, v48 offset1:32
	ds_write2_b32 v142, v33, v49 offset0:4 offset1:36
	ds_write2_b32 v143, v34, v50 offset0:8 offset1:40
	ds_write2_b32 v144, v35, v51 offset0:12 offset1:44
	ds_write2_b32 v145, v36, v52 offset0:32 offset1:64
	ds_write2_b32 v146, v37, v53 offset0:36 offset1:68
	ds_write2_b32 v147, v38, v54 offset0:40 offset1:72
	ds_write2_b32 v148, v39, v55 offset0:44 offset1:76
	ds_write2_b32 v149, v40, v56 offset0:64 offset1:96
	ds_write2_b32 v150, v41, v57 offset0:68 offset1:100
	ds_write2_b32 v151, v42, v58 offset0:72 offset1:104
	ds_write2_b32 v152, v43, v59 offset0:76 offset1:108
	ds_write2_b32 v153, v44, v60 offset0:96 offset1:128
	ds_write2_b32 v154, v45, v61 offset0:100 offset1:132
	ds_write2_b32 v155, v46, v62 offset0:104 offset1:136
	ds_write2_b32 v156, v47, v63 offset0:108 offset1:140
	ds_write2_b32 v157, v0, v16 offset0:128 offset1:160
	ds_write2_b32 v158, v1, v17 offset0:132 offset1:164
	ds_write2_b32 v159, v2, v18 offset0:136 offset1:168
	ds_write2_b32 v160, v3, v19 offset0:140 offset1:172
	ds_write2_b32 v161, v4, v20 offset0:160 offset1:192
	ds_write2_b32 v162, v5, v21 offset0:164 offset1:196
	ds_write2_b32 v163, v6, v22 offset0:168 offset1:200
	ds_write2_b32 v164, v7, v23 offset0:172 offset1:204
	ds_write2_b32 v165, v8, v24 offset0:192 offset1:224
	ds_write2_b32 v166, v9, v25 offset0:196 offset1:228
	ds_write2_b32 v167, v10, v26 offset0:200 offset1:232
	ds_write2_b32 v168, v11, v27 offset0:204 offset1:236
	ds_write2_b32 v169, v12, v28 offset0:96 offset1:128
	ds_write2_b32 v170, v13, v29 offset0:100 offset1:132
	ds_write2_b32 v171, v14, v30 offset0:104 offset1:136
	ds_write2_b32 v172, v15, v31 offset0:108 offset1:140
	s_waitcnt lgkmcnt(0)
	s_barrier
; __device__ __forceinline__ unsigned fkey(float f) { unsigned u = __float_as_uint(f); return (u & 0x80000000u) ? ~u : (u | 0x80000000u); }
; __device__ __forceinline__ float fkey_inv(unsigned k) { unsigned u = (k & 0x80000000u) ? (k & 0x7fffffffu) : ~k; return __uint_as_float(u); }
; __device__ __forceinline__ void insert16(unsigned (&L)[16], unsigned x) {
; #pragma unroll
;   for (int i = 0; i < 16; ++i) { const unsigned hi = x > L[i] ? x : L[i]; x = x > L[i] ? L[i] : x; L[i] = hi; }
; }
; __device__ __forceinline__ void sort16_desc(unsigned (&a)[16]) {
; #pragma unroll
;   for (int k = 2; k <= 16; k <<= 1)
; #pragma unroll
;     for (int j = k >> 1; j > 0; j >>= 1)
; #pragma unroll
;       for (int i = 0; i < 16; ++i) {
;         const int l = i ^ j;
;         if (l > i) { if ((i & k) == 0) cswap_desc(a[i], a[l]); else cswap_desc(a[l], a[i]); }
;       }
; __device__ void phase_peer_select(const Params& p, char* lds) {
;     ...
;       const float* sp = S + tok * 260 + c * 128 + half * 64;
; #pragma unroll
;       for (int grp = 0; grp < 4; ++grp) {
;         unsigned G[16];
; #pragma unroll
;         for (int n4 = 0; n4 < 4; ++n4) {
;           const f32x4 v = *(const f32x4*)(sp + grp * 16 + n4 * 4);
;           const unsigned ib = (unsigned)(127 - (half * 64 + grp * 16 + n4 * 4));
; #pragma unroll
;           for (int e = 0; e < 4; ++e) G[n4 * 4 + e] = (fkey(v[e]) & ~127u) | (ib - e);
;         }
;         sort16_desc(G);
;         if (grp == 0) {
; #pragma unroll
;           for (int i = 0; i < 16; ++i) L[i] = G[i];
;         } else merge16_desc<true>(L, G);
	ds_read_b128 v[0:3], v72
	ds_read_b128 v[4:7], v72 offset:16
	ds_read_b128 v[8:11], v72 offset:32
	ds_read_b128 v[12:15], v72 offset:48
	ds_read_b128 v[24:27], v72 offset:64
	s_waitcnt lgkmcnt(4)
	v_not_b32_e32 v16, v0
	v_or_b32_e32 v17, 0x80000000, v0
	v_cmp_gt_i32_e32 vcc, 0, v0
	s_waitcnt lgkmcnt(0)
	v_not_b32_e32 v28, v24
	v_cndmask_b32_e32 v0, v17, v16, vcc
	v_not_b32_e32 v16, v1
	v_or_b32_e32 v17, 0x80000000, v1
	v_cmp_gt_i32_e32 vcc, 0, v1
	v_not_b32_e32 v29, v27
	v_and_or_b32 v0, v0, s38, v78
	v_cndmask_b32_e32 v1, v17, v16, vcc
	v_not_b32_e32 v16, v2
	v_or_b32_e32 v17, 0x80000000, v2
	v_cmp_gt_i32_e32 vcc, 0, v2
	v_and_or_b32 v1, v1, s38, v79
	s_nop 0
	v_cndmask_b32_e32 v2, v17, v16, vcc
	v_not_b32_e32 v16, v3
	v_or_b32_e32 v17, 0x80000000, v3
	v_cmp_gt_i32_e32 vcc, 0, v3
	v_and_or_b32 v2, v2, s38, v80
	s_nop 0
	v_cndmask_b32_e32 v3, v17, v16, vcc
	v_not_b32_e32 v16, v4
	v_or_b32_e32 v17, 0x80000000, v4
	v_cmp_gt_i32_e32 vcc, 0, v4
	v_and_or_b32 v3, v3, s38, v81
	s_nop 0
	v_cndmask_b32_e32 v4, v17, v16, vcc
	v_not_b32_e32 v16, v5
	v_or_b32_e32 v17, 0x80000000, v5
	v_cmp_gt_i32_e32 vcc, 0, v5
	v_and_or_b32 v4, v4, s38, v82
	s_nop 0
	v_cndmask_b32_e32 v5, v17, v16, vcc
	v_not_b32_e32 v16, v6
	v_or_b32_e32 v17, 0x80000000, v6
	v_cmp_gt_i32_e32 vcc, 0, v6
	v_and_or_b32 v5, v5, s38, v83
	s_nop 0
	v_cndmask_b32_e32 v6, v17, v16, vcc
	v_not_b32_e32 v16, v7
	v_or_b32_e32 v17, 0x80000000, v7
	v_cmp_gt_i32_e32 vcc, 0, v7
	v_and_or_b32 v6, v6, s38, v84
	s_nop 0
	v_cndmask_b32_e32 v7, v17, v16, vcc
	v_not_b32_e32 v16, v8
	v_or_b32_e32 v17, 0x80000000, v8
	v_cmp_gt_i32_e32 vcc, 0, v8
	v_and_or_b32 v7, v7, s38, v85
	s_nop 0
	v_cndmask_b32_e32 v8, v17, v16, vcc
	v_not_b32_e32 v16, v9
	v_or_b32_e32 v17, 0x80000000, v9
	v_cmp_gt_i32_e32 vcc, 0, v9
	v_and_or_b32 v8, v8, s38, v86
	s_nop 0
	v_cndmask_b32_e32 v9, v17, v16, vcc
	v_not_b32_e32 v16, v10
	v_or_b32_e32 v17, 0x80000000, v10
	v_cmp_gt_i32_e32 vcc, 0, v10
	v_and_or_b32 v9, v9, s38, v87
	s_nop 0
	v_cndmask_b32_e32 v10, v17, v16, vcc
	v_not_b32_e32 v16, v11
	v_or_b32_e32 v17, 0x80000000, v11
	v_cmp_gt_i32_e32 vcc, 0, v11
	v_and_or_b32 v10, v10, s38, v88
	s_nop 0
	v_cndmask_b32_e32 v11, v17, v16, vcc
	v_not_b32_e32 v16, v12
	v_or_b32_e32 v17, 0x80000000, v12
	v_cmp_gt_i32_e32 vcc, 0, v12
	v_and_or_b32 v11, v11, s38, v89
	s_nop 0
	v_cndmask_b32_e32 v12, v17, v16, vcc
	v_not_b32_e32 v16, v13
	v_or_b32_e32 v17, 0x80000000, v13
	v_cmp_gt_i32_e32 vcc, 0, v13
	v_and_or_b32 v12, v12, s38, v90
	s_nop 0
	v_cndmask_b32_e32 v13, v17, v16, vcc
	v_not_b32_e32 v16, v14
	v_or_b32_e32 v17, 0x80000000, v14
	v_cmp_gt_i32_e32 vcc, 0, v14
	v_and_or_b32 v13, v13, s38, v91
	s_nop 0
	v_cndmask_b32_e32 v14, v17, v16, vcc
	v_not_b32_e32 v16, v15
	v_or_b32_e32 v17, 0x80000000, v15
	v_cmp_gt_i32_e32 vcc, 0, v15
	v_and_or_b32 v14, v14, s38, v92
	s_nop 0
	v_cndmask_b32_e32 v15, v17, v16, vcc
	v_cmp_gt_i32_e32 vcc, 0, v24
	v_or_b32_e32 v24, 0x80000000, v24
	v_and_or_b32 v15, v15, s38, v93
	v_cndmask_b32_e32 v24, v24, v28, vcc
	v_cmp_gt_i32_e32 vcc, 0, v25
	v_not_b32_e32 v28, v25
	v_or_b32_e32 v25, 0x80000000, v25
	v_cndmask_b32_e32 v25, v25, v28, vcc
	v_cmp_gt_i32_e32 vcc, 0, v27
	v_or_b32_e32 v27, 0x80000000, v27
	v_and_or_b32 v24, v24, s38, v94
	v_cndmask_b32_e32 v27, v27, v29, vcc
	v_cmp_gt_i32_e32 vcc, 0, v26
	v_not_b32_e32 v29, v26
	v_or_b32_e32 v26, 0x80000000, v26
	v_cndmask_b32_e32 v26, v26, v29, vcc
	v_and_or_b32 v25, v25, s38, v95
	v_and_or_b32 v27, v27, s38, v96
	v_and_or_b32 v26, v26, s38, v97
	v_max_u32_e32 v28, v24, v25
	v_min_u32_e32 v29, v27, v26
	v_min_u32_e32 v31, v24, v25
	v_max_u32_e32 v32, v27, v26
	ds_read_b128 v[24:27], v72 offset:80
	v_max_u32_e32 v30, v28, v29
	v_max_u32_e32 v33, v31, v32
	v_max_u32_e32 v34, v30, v33
	v_min_u32_e32 v30, v30, v33
	s_waitcnt lgkmcnt(0)
	v_cmp_gt_i32_e32 vcc, 0, v27
	v_not_b32_e32 v35, v27
	v_or_b32_e32 v27, 0x80000000, v27
	v_cndmask_b32_e32 v27, v27, v35, vcc
	v_cmp_gt_i32_e32 vcc, 0, v26
	v_not_b32_e32 v35, v26
	v_or_b32_e32 v26, 0x80000000, v26
	v_cndmask_b32_e32 v26, v26, v35, vcc
	v_cmp_gt_i32_e32 vcc, 0, v24
	v_not_b32_e32 v36, v24
	v_or_b32_e32 v24, 0x80000000, v24
	v_cndmask_b32_e32 v24, v24, v36, vcc
	v_cmp_gt_i32_e32 vcc, 0, v25
	v_not_b32_e32 v36, v25
	v_or_b32_e32 v25, 0x80000000, v25
	v_cndmask_b32_e32 v25, v25, v36, vcc
	v_and_or_b32 v27, v27, s38, v98
	v_and_or_b32 v26, v26, s38, v99
	v_and_or_b32 v24, v24, s38, v100
	v_and_or_b32 v25, v25, s38, v101
	v_max_u32_e32 v35, v27, v26
	v_min_u32_e32 v36, v24, v25
	v_min_u32_e32 v26, v27, v26
	v_max_u32_e32 v24, v24, v25
	v_min_u32_e32 v37, v35, v36
	v_min_u32_e32 v25, v26, v24
	v_min_u32_e32 v27, v28, v29
	v_min_u32_e32 v28, v31, v32
	v_max_u32_e32 v31, v35, v36
	v_max_u32_e32 v24, v26, v24
	v_min_u32_e32 v38, v37, v25
	v_max_u32_e32 v29, v27, v28
	v_min_u32_e32 v32, v31, v24
	v_max_u32_e32 v33, v37, v25
	v_min_u32_e32 v28, v27, v28
	v_max_u32_e32 v31, v31, v24
	ds_read_b128 v[24:27], v72 offset:112
	v_max_u32_e32 v16, v0, v1
	v_min_u32_e32 v0, v0, v1
	v_max_u32_e32 v1, v3, v2
	v_min_u32_e32 v2, v3, v2
	s_waitcnt lgkmcnt(0)
	v_cmp_gt_i32_e32 vcc, 0, v27
	v_not_b32_e32 v43, v27
	v_or_b32_e32 v27, 0x80000000, v27
	v_cndmask_b32_e32 v27, v27, v43, vcc
	v_cmp_gt_i32_e32 vcc, 0, v26
	v_not_b32_e32 v43, v26
	v_or_b32_e32 v26, 0x80000000, v26
	v_cndmask_b32_e32 v26, v26, v43, vcc
	v_cmp_gt_i32_e32 vcc, 0, v24
	v_not_b32_e32 v44, v24
	v_or_b32_e32 v24, 0x80000000, v24
	v_cndmask_b32_e32 v24, v24, v44, vcc
	v_cmp_gt_i32_e32 vcc, 0, v25
	v_not_b32_e32 v44, v25
	v_or_b32_e32 v25, 0x80000000, v25
	v_cndmask_b32_e32 v25, v25, v44, vcc
	v_and_or_b32 v27, v27, s38, v102
	v_and_or_b32 v26, v26, s38, v103
	v_and_or_b32 v24, v24, s38, v104
	v_and_or_b32 v25, v25, s38, v105
	v_max_u32_e32 v43, v27, v26
	v_min_u32_e32 v44, v24, v25
	v_min_u32_e32 v46, v27, v26
	v_max_u32_e32 v47, v24, v25
	ds_read_b128 v[24:27], v72 offset:96
	v_max_u32_e32 v3, v4, v5
	v_min_u32_e32 v4, v4, v5
	v_max_u32_e32 v5, v7, v6
	v_min_u32_e32 v6, v7, v6
	s_waitcnt lgkmcnt(0)
; __device__ __forceinline__ unsigned fkey(float f) { unsigned u = __float_as_uint(f); return (u & 0x80000000u) ? ~u : (u | 0x80000000u); }
; __device__ __forceinline__ void sort16_desc(unsigned (&a)[16]) {
; #pragma unroll
;   for (int k = 2; k <= 16; k <<= 1)
; #pragma unroll
;     for (int j = k >> 1; j > 0; j >>= 1)
; #pragma unroll
;       for (int i = 0; i < 16; ++i) {
;         const int l = i ^ j;
;         if (l > i) { if ((i & k) == 0) cswap_desc(a[i], a[l]); else cswap_desc(a[l], a[i]); }
;       }
; __device__ void phase_peer_select(const Params& p, char* lds) {
;     ...
;       for (int grp = 0; grp < 4; ++grp) {
;         unsigned G[16];
; #pragma unroll
;         for (int n4 = 0; n4 < 4; ++n4) {
;           const f32x4 v = *(const f32x4*)(sp + grp * 16 + n4 * 4);
;           const unsigned ib = (unsigned)(127 - (half * 64 + grp * 16 + n4 * 4));
; #pragma unroll
;           for (int e = 0; e < 4; ++e) G[n4 * 4 + e] = (fkey(v[e]) & ~127u) | (ib - e);
;         }
;         sort16_desc(G);
;         if (grp == 0) {
; #pragma unroll
;           for (int i = 0; i < 16; ++i) L[i] = G[i];
;         } else merge16_desc<true>(L, G);
	v_cmp_gt_i32_e32 vcc, 0, v24
	v_not_b32_e32 v50, v24
	v_or_b32_e32 v24, 0x80000000, v24
	v_cndmask_b32_e32 v24, v24, v50, vcc
	v_cmp_gt_i32_e32 vcc, 0, v25
	v_not_b32_e32 v50, v25
	v_or_b32_e32 v25, 0x80000000, v25
	v_cndmask_b32_e32 v25, v25, v50, vcc
	v_cmp_gt_i32_e32 vcc, 0, v27
	v_not_b32_e32 v51, v27
	v_or_b32_e32 v27, 0x80000000, v27
	v_cndmask_b32_e32 v27, v27, v51, vcc
	v_cmp_gt_i32_e32 vcc, 0, v26
	v_not_b32_e32 v51, v26
	v_or_b32_e32 v26, 0x80000000, v26
	v_cndmask_b32_e32 v26, v26, v51, vcc
	v_and_or_b32 v24, v24, s38, v106
	v_and_or_b32 v25, v25, s38, v107
	v_and_or_b32 v27, v27, s38, v108
	v_and_or_b32 v26, v26, s38, v109
	v_max_u32_e32 v7, v8, v9
	v_min_u32_e32 v8, v8, v9
	v_max_u32_e32 v9, v11, v10
	v_min_u32_e32 v10, v11, v10
	v_max_u32_e32 v11, v12, v13
	v_min_u32_e32 v12, v12, v13
	v_max_u32_e32 v13, v15, v14
	v_min_u32_e32 v14, v15, v14
	v_max_u32_e32 v50, v24, v25
	v_min_u32_e32 v51, v27, v26
	v_min_u32_e32 v24, v24, v25
	v_max_u32_e32 v25, v27, v26
	v_max_u32_e32 v15, v16, v2
	v_min_u32_e32 v2, v16, v2
	v_max_u32_e32 v16, v0, v1
	v_min_u32_e32 v0, v0, v1
	v_max_u32_e32 v1, v6, v3
	v_min_u32_e32 v3, v6, v3
	v_max_u32_e32 v6, v5, v4
	v_min_u32_e32 v4, v5, v4
	v_max_u32_e32 v5, v7, v10
	v_min_u32_e32 v7, v7, v10
	v_max_u32_e32 v10, v8, v9
	v_min_u32_e32 v8, v8, v9
	v_max_u32_e32 v9, v14, v11
	v_min_u32_e32 v11, v14, v11
	v_max_u32_e32 v14, v13, v12
	v_min_u32_e32 v12, v13, v12
	v_max_u32_e32 v45, v43, v44
	v_max_u32_e32 v48, v46, v47
	v_min_u32_e32 v52, v50, v51
	v_min_u32_e32 v26, v24, v25
	v_min_u32_e32 v43, v43, v44
	v_min_u32_e32 v44, v46, v47
	v_max_u32_e32 v47, v50, v51
	v_max_u32_e32 v24, v24, v25
	v_max_u32_e32 v13, v15, v16
	v_min_u32_e32 v15, v15, v16
	v_max_u32_e32 v16, v2, v0
	v_min_u32_e32 v0, v2, v0
	v_max_u32_e32 v2, v4, v3
	v_min_u32_e32 v3, v4, v3
	v_max_u32_e32 v4, v6, v1
	v_min_u32_e32 v1, v6, v1
	v_max_u32_e32 v6, v5, v10
	v_min_u32_e32 v5, v5, v10
	v_max_u32_e32 v10, v7, v8
	v_min_u32_e32 v7, v7, v8
	v_max_u32_e32 v8, v12, v11
	v_min_u32_e32 v11, v12, v11
	v_max_u32_e32 v12, v14, v9
	v_min_u32_e32 v9, v14, v9
	v_max_u32_e32 v49, v45, v48
	v_min_u32_e32 v27, v52, v26
	v_max_u32_e32 v46, v43, v44
	v_min_u32_e32 v25, v47, v24
	v_min_u32_e32 v45, v45, v48
	v_max_u32_e32 v26, v52, v26
	v_min_u32_e32 v43, v43, v44
	v_max_u32_e32 v24, v47, v24
	v_max_u32_e32 v14, v13, v3
	v_min_u32_e32 v3, v13, v3
	v_max_u32_e32 v13, v15, v2
	v_min_u32_e32 v2, v15, v2
	v_max_u32_e32 v15, v16, v1
	v_min_u32_e32 v1, v16, v1
	v_max_u32_e32 v16, v0, v4
	v_min_u32_e32 v0, v0, v4
	v_max_u32_e32 v4, v11, v6
	v_min_u32_e32 v6, v11, v6
	v_max_u32_e32 v11, v8, v5
	v_min_u32_e32 v5, v8, v5
	v_max_u32_e32 v8, v9, v10
	v_min_u32_e32 v9, v9, v10
	v_max_u32_e32 v10, v12, v7
	v_min_u32_e32 v7, v12, v7
	v_max_u32_e32 v39, v34, v38
	v_max_u32_e32 v35, v29, v32
	v_max_u32_e32 v37, v30, v33
	v_max_u32_e32 v40, v28, v31
	v_min_u32_e32 v53, v49, v27
	v_min_u32_e32 v50, v46, v25
	v_min_u32_e32 v48, v45, v26
	v_min_u32_e32 v44, v43, v24
	v_min_u32_e32 v34, v34, v38
	v_min_u32_e32 v29, v29, v32
	v_min_u32_e32 v30, v30, v33
	v_min_u32_e32 v28, v28, v31
	v_max_u32_e32 v27, v49, v27
	v_max_u32_e32 v25, v46, v25
	v_max_u32_e32 v26, v45, v26
	v_max_u32_e32 v24, v43, v24
	v_max_u32_e32 v12, v14, v15
	v_min_u32_e32 v14, v14, v15
	v_max_u32_e32 v15, v13, v16
	v_min_u32_e32 v13, v13, v16
	v_max_u32_e32 v16, v3, v1
	v_min_u32_e32 v1, v3, v1
	v_max_u32_e32 v3, v2, v0
	v_min_u32_e32 v0, v2, v0
	v_max_u32_e32 v2, v9, v6
	v_min_u32_e32 v6, v9, v6
	v_max_u32_e32 v9, v7, v5
	v_min_u32_e32 v5, v7, v5
	v_max_u32_e32 v7, v8, v4
	v_min_u32_e32 v4, v8, v4
	v_max_u32_e32 v8, v10, v11
	v_min_u32_e32 v10, v10, v11
	v_max_u32_e32 v36, v39, v35
	v_max_u32_e32 v41, v37, v40
	v_min_u32_e32 v51, v53, v50
	v_min_u32_e32 v47, v48, v44
	v_max_u32_e32 v32, v34, v29
	v_max_u32_e32 v31, v30, v28
	v_min_u32_e32 v38, v27, v25
	v_min_u32_e32 v43, v26, v24
	v_min_u32_e32 v35, v39, v35
	v_min_u32_e32 v37, v37, v40
	v_max_u32_e32 v40, v53, v50
	v_max_u32_e32 v44, v48, v44
	v_min_u32_e32 v29, v34, v29
	v_min_u32_e32 v28, v30, v28
	v_max_u32_e32 v25, v27, v25
	v_max_u32_e32 v24, v26, v24
	v_max_u32_e32 v11, v12, v15
	v_min_u32_e32 v12, v12, v15
	v_max_u32_e32 v15, v14, v13
	v_min_u32_e32 v13, v14, v13
	v_max_u32_e32 v14, v16, v3
	v_min_u32_e32 v3, v16, v3
	v_max_u32_e32 v16, v1, v0
	v_min_u32_e32 v0, v1, v0
	v_max_u32_e32 v1, v5, v6
	v_min_u32_e32 v5, v5, v6
	v_max_u32_e32 v6, v9, v2
	v_min_u32_e32 v2, v9, v2
	v_max_u32_e32 v9, v10, v4
	v_min_u32_e32 v4, v10, v4
	v_max_u32_e32 v10, v8, v7
	v_min_u32_e32 v7, v8, v7
	v_max_u32_e32 v42, v36, v41
	v_min_u32_e32 v52, v51, v47
	v_max_u32_e32 v33, v32, v31
	v_min_u32_e32 v45, v38, v43
	v_max_u32_e32 v39, v35, v37
	v_min_u32_e32 v48, v40, v44
	v_max_u32_e32 v30, v29, v28
	v_min_u32_e32 v26, v25, v24
	v_min_u32_e32 v36, v36, v41
	v_max_u32_e32 v41, v51, v47
	v_min_u32_e32 v31, v32, v31
	v_max_u32_e32 v32, v38, v43
	v_min_u32_e32 v35, v35, v37
	v_max_u32_e32 v37, v40, v44
	v_min_u32_e32 v28, v29, v28
	v_max_u32_e32 v24, v25, v24
	v_max_u32_e32 v8, v11, v5
	v_min_u32_e32 v5, v11, v5
	v_max_u32_e32 v11, v12, v1
	v_min_u32_e32 v1, v12, v1
	v_max_u32_e32 v12, v15, v2
	v_min_u32_e32 v2, v15, v2
	v_max_u32_e32 v15, v13, v6
	v_min_u32_e32 v6, v13, v6
	v_max_u32_e32 v13, v14, v4
	v_min_u32_e32 v4, v14, v4
	v_max_u32_e32 v14, v3, v9
	v_min_u32_e32 v3, v3, v9
	v_max_u32_e32 v9, v16, v7
	v_min_u32_e32 v7, v16, v7
	v_max_u32_e32 v16, v0, v10
	v_min_u32_e32 v0, v0, v10
	v_min_u32_e32 v54, v42, v52
	v_min_u32_e32 v46, v33, v45
	v_min_u32_e32 v50, v39, v48
	v_min_u32_e32 v27, v30, v26
	v_min_u32_e32 v47, v36, v41
	v_min_u32_e32 v38, v31, v32
	v_min_u32_e32 v40, v35, v37
; __device__ __forceinline__ unsigned fkey(float f) { unsigned u = __float_as_uint(f); return (u & 0x80000000u) ? ~u : (u | 0x80000000u); }
; template <bool SORT>
; __device__ __forceinline__ void merge16_desc(unsigned (&a)[16], const unsigned (&b)[16]) {
; #pragma unroll
;   for (int i = 0; i < 16; ++i) a[i] = a[i] > b[15 - i] ? a[i] : b[15 - i];
;   if (SORT) {
; #pragma unroll
;     for (int j = 8; j > 0; j >>= 1)
; #pragma unroll
;       for (int i = 0; i < 16; ++i) { const int l = i ^ j; if (l > i) cswap_desc(a[i], a[l]); }
;   }
; __device__ void phase_peer_select(const Params& p, char* lds) {
;     ...
;       for (int grp = 0; grp < 4; ++grp) {
;         unsigned G[16];
; #pragma unroll
;         for (int n4 = 0; n4 < 4; ++n4) {
;           const f32x4 v = *(const f32x4*)(sp + grp * 16 + n4 * 4);
;           const unsigned ib = (unsigned)(127 - (half * 64 + grp * 16 + n4 * 4));
; #pragma unroll
;           for (int e = 0; e < 4; ++e) G[n4 * 4 + e] = (fkey(v[e]) & ~127u) | (ib - e);
;         }
;         sort16_desc(G);
;         if (grp == 0) {
; #pragma unroll
;           for (int i = 0; i < 16; ++i) L[i] = G[i];
;         } else merge16_desc<true>(L, G);
	v_min_u32_e32 v25, v28, v24
	v_max_u32_e32 v42, v42, v52
	v_max_u32_e32 v33, v33, v45
	v_max_u32_e32 v39, v39, v48
	v_max_u32_e32 v26, v30, v26
	v_max_u32_e32 v36, v36, v41
	v_max_u32_e32 v31, v31, v32
	v_max_u32_e32 v35, v35, v37
	v_max_u32_e32 v24, v28, v24
	v_max_u32_e32 v10, v8, v13
	v_min_u32_e32 v13, v8, v13
	v_max_u32_e32 v8, v11, v14
	v_min_u32_e32 v11, v11, v14
	v_max_u32_e32 v14, v12, v9
	v_min_u32_e32 v9, v12, v9
	v_max_u32_e32 v17, v15, v16
	v_min_u32_e32 v15, v15, v16
	v_max_u32_e32 v16, v5, v4
	v_min_u32_e32 v18, v5, v4
	v_max_u32_e32 v19, v1, v3
	v_min_u32_e32 v20, v1, v3
	v_max_u32_e32 v3, v2, v7
	v_min_u32_e32 v21, v2, v7
	v_min_u32_e32 v22, v6, v0
	v_min_u32_e32 v49, v54, v46
	v_min_u32_e32 v34, v50, v27
	v_min_u32_e32 v43, v47, v38
	v_min_u32_e32 v29, v40, v25
	v_max_u32_e32 v46, v54, v46
	v_max_u32_e32 v27, v50, v27
	v_max_u32_e32 v38, v47, v38
	v_max_u32_e32 v25, v40, v25
	v_min_u32_e32 v45, v42, v33
	v_min_u32_e32 v30, v39, v26
	v_min_u32_e32 v32, v36, v31
	v_min_u32_e32 v28, v35, v24
	v_max_u32_e32 v33, v42, v33
	v_max_u32_e32 v26, v39, v26
	v_max_u32_e32 v31, v36, v31
	v_max_u32_e32 v24, v35, v24
	v_max_u32_e32 v7, v6, v0
	v_max_u32_e32 v5, v13, v9
	v_min_u32_e32 v1, v13, v9
	v_max_u32_e32 v13, v11, v15
	v_min_u32_e32 v9, v11, v15
	v_max_u32_e32 v6, v16, v3
	v_min_u32_e32 v2, v16, v3
	v_min_u32_e32 v3, v18, v21
	v_min_u32_e32 v11, v20, v22
	v_min_u32_e32 v53, v49, v34
	v_max_u32_e32 v34, v49, v34
	v_min_u32_e32 v49, v46, v27
	v_min_u32_e32 v40, v38, v25
	v_max_u32_e32 v27, v46, v27
	v_max_u32_e32 v25, v38, v25
	v_min_u32_e32 v39, v33, v26
	v_min_u32_e32 v35, v31, v24
	v_max_u32_e32 v26, v33, v26
	v_max_u32_e32 v24, v31, v24
	v_max_u32_e32 v15, v20, v22
	v_min_u32_e32 v20, v1, v9
	v_min_u32_e32 v16, v3, v11
	v_min_u32_e32 v38, v27, v25
	v_min_u32_e32 v31, v26, v24
	v_max3_u32 v1, v1, v9, v38
	v_max3_u32 v9, v20, v27, v25
	v_max3_u32 v3, v3, v11, v31
	v_max3_u32 v11, v16, v26, v24
	ds_read_b128 v[24:27], v72 offset:128
	v_max_u32_e32 v4, v10, v14
	v_min_u32_e32 v0, v10, v14
	v_min_u32_e32 v10, v19, v7
	v_min_u32_e32 v46, v45, v30
	v_min_u32_e32 v37, v32, v28
	v_max_u32_e32 v30, v45, v30
	v_max_u32_e32 v28, v32, v28
	v_max_u32_e32 v14, v19, v7
	v_max_u32_e32 v7, v18, v21
	v_min_u32_e32 v18, v2, v10
	v_min_u32_e32 v32, v30, v28
	v_max_u32_e32 v12, v8, v17
	v_min_u32_e32 v8, v8, v17
	v_min_u32_e32 v44, v43, v29
	v_max_u32_e32 v29, v43, v29
	v_max3_u32 v2, v2, v10, v32
	v_max3_u32 v10, v18, v30, v28
	s_waitcnt lgkmcnt(0)
	v_cmp_gt_i32_e32 vcc, 0, v24
	v_not_b32_e32 v28, v24
	v_or_b32_e32 v24, 0x80000000, v24
	v_min_u32_e32 v22, v0, v8
	v_min_u32_e32 v43, v34, v29
	v_cndmask_b32_e32 v24, v24, v28, vcc
	v_cmp_gt_i32_e32 vcc, 0, v25
	v_not_b32_e32 v28, v25
	v_or_b32_e32 v25, 0x80000000, v25
	v_max3_u32 v0, v0, v8, v43
	v_max3_u32 v8, v22, v34, v29
	v_cndmask_b32_e32 v25, v25, v28, vcc
	v_cmp_gt_i32_e32 vcc, 0, v27
	v_not_b32_e32 v29, v27
	v_or_b32_e32 v27, 0x80000000, v27
	v_cndmask_b32_e32 v27, v27, v29, vcc
	v_cmp_gt_i32_e32 vcc, 0, v26
	v_not_b32_e32 v29, v26
	v_or_b32_e32 v26, 0x80000000, v26
	v_cndmask_b32_e32 v26, v26, v29, vcc
	v_and_or_b32 v24, v24, s38, v110
	v_and_or_b32 v25, v25, s38, v111
	v_and_or_b32 v27, v27, s38, v112
	v_and_or_b32 v26, v26, s38, v113
	v_max_u32_e32 v28, v24, v25
	v_min_u32_e32 v29, v27, v26
	v_min_u32_e32 v31, v24, v25
	v_max_u32_e32 v32, v27, v26
	ds_read_b128 v[24:27], v72 offset:144
	v_min_u32_e32 v17, v7, v15
	v_min_u32_e32 v36, v39, v35
	v_max3_u32 v7, v7, v15, v36
	v_max3_u32 v15, v17, v39, v35
	s_waitcnt lgkmcnt(0)
	v_cmp_gt_i32_e32 vcc, 0, v27
	v_not_b32_e32 v35, v27
	v_or_b32_e32 v27, 0x80000000, v27
	v_cndmask_b32_e32 v27, v27, v35, vcc
	v_cmp_gt_i32_e32 vcc, 0, v26
	v_not_b32_e32 v35, v26
	v_or_b32_e32 v26, 0x80000000, v26
	v_cndmask_b32_e32 v26, v26, v35, vcc
	v_cmp_gt_i32_e32 vcc, 0, v24
	v_not_b32_e32 v36, v24
	v_or_b32_e32 v24, 0x80000000, v24
	v_cndmask_b32_e32 v24, v24, v36, vcc
	v_cmp_gt_i32_e32 vcc, 0, v25
	v_not_b32_e32 v36, v25
	v_or_b32_e32 v25, 0x80000000, v25
	v_cndmask_b32_e32 v25, v25, v36, vcc
	v_and_or_b32 v27, v27, s38, v114
	v_and_or_b32 v26, v26, s38, v115
	v_and_or_b32 v24, v24, s38, v116
	v_and_or_b32 v25, v25, s38, v117
	v_min_u32_e32 v19, v6, v14
	v_min_u32_e32 v41, v46, v37
	v_max_u32_e32 v35, v27, v26
	v_min_u32_e32 v36, v24, v25
	v_min_u32_e32 v26, v27, v26
	v_max_u32_e32 v24, v24, v25
	v_max3_u32 v6, v6, v14, v41
	v_max3_u32 v14, v19, v46, v37
	v_max_u32_e32 v30, v28, v29
	v_max_u32_e32 v33, v31, v32
	v_min_u32_e32 v37, v35, v36
	v_min_u32_e32 v25, v26, v24
	v_min_u32_e32 v27, v28, v29
	v_min_u32_e32 v28, v31, v32
	v_max_u32_e32 v31, v35, v36
	v_max_u32_e32 v24, v26, v24
	v_max_u32_e32 v34, v30, v33
	v_min_u32_e32 v38, v37, v25
	v_max_u32_e32 v29, v27, v28
	v_min_u32_e32 v32, v31, v24
	v_min_u32_e32 v30, v30, v33
	v_max_u32_e32 v33, v37, v25
	v_min_u32_e32 v28, v27, v28
	v_max_u32_e32 v31, v31, v24
	ds_read_b128 v[24:27], v72 offset:176
	v_min_u32_e32 v23, v4, v12
	v_min_u32_e32 v51, v53, v44
	v_max3_u32 v4, v4, v12, v51
	v_max3_u32 v12, v23, v53, v44
	s_waitcnt lgkmcnt(0)
	v_cmp_gt_i32_e32 vcc, 0, v27
	v_not_b32_e32 v43, v27
	v_or_b32_e32 v27, 0x80000000, v27
	v_cndmask_b32_e32 v27, v27, v43, vcc
	v_cmp_gt_i32_e32 vcc, 0, v26
	v_not_b32_e32 v43, v26
	v_or_b32_e32 v26, 0x80000000, v26
	v_cndmask_b32_e32 v26, v26, v43, vcc
	v_cmp_gt_i32_e32 vcc, 0, v24
	v_not_b32_e32 v44, v24
	v_or_b32_e32 v24, 0x80000000, v24
	v_cndmask_b32_e32 v24, v24, v44, vcc
	v_cmp_gt_i32_e32 vcc, 0, v25
	v_not_b32_e32 v44, v25
	v_or_b32_e32 v25, 0x80000000, v25
	v_cndmask_b32_e32 v25, v25, v44, vcc
	v_min_u32_e32 v47, v49, v40
	v_and_or_b32 v27, v27, s38, v118
	v_and_or_b32 v26, v26, s38, v119
	v_and_or_b32 v24, v24, s38, v120
	v_and_or_b32 v25, v25, s38, v121
	v_min_u32_e32 v21, v5, v13
	v_max3_u32 v5, v5, v13, v47
	v_max_u32_e32 v43, v27, v26
	v_min_u32_e32 v44, v24, v25
	v_min_u32_e32 v46, v27, v26
	v_max_u32_e32 v47, v24, v25
	ds_read_b128 v[24:27], v72 offset:160
	v_max_u32_e32 v45, v43, v44
	v_max_u32_e32 v48, v46, v47
	v_min_u32_e32 v43, v43, v44
	v_min_u32_e32 v44, v46, v47
	s_waitcnt lgkmcnt(0)
; __device__ __forceinline__ unsigned fkey(float f) { unsigned u = __float_as_uint(f); return (u & 0x80000000u) ? ~u : (u | 0x80000000u); }
; template <bool SORT>
; __device__ __forceinline__ void merge16_desc(unsigned (&a)[16], const unsigned (&b)[16]) {
; #pragma unroll
;   for (int i = 0; i < 16; ++i) a[i] = a[i] > b[15 - i] ? a[i] : b[15 - i];
;   if (SORT) {
; #pragma unroll
;     for (int j = 8; j > 0; j >>= 1)
; #pragma unroll
;       for (int i = 0; i < 16; ++i) { const int l = i ^ j; if (l > i) cswap_desc(a[i], a[l]); }
;   }
; __device__ void phase_peer_select(const Params& p, char* lds) {
;     ...
;       for (int grp = 0; grp < 4; ++grp) {
;         unsigned G[16];
; #pragma unroll
;         for (int n4 = 0; n4 < 4; ++n4) {
;           const f32x4 v = *(const f32x4*)(sp + grp * 16 + n4 * 4);
;           const unsigned ib = (unsigned)(127 - (half * 64 + grp * 16 + n4 * 4));
; #pragma unroll
;           for (int e = 0; e < 4; ++e) G[n4 * 4 + e] = (fkey(v[e]) & ~127u) | (ib - e);
;         }
;         sort16_desc(G);
;         if (grp == 0) {
; #pragma unroll
;           for (int i = 0; i < 16; ++i) L[i] = G[i];
;         } else merge16_desc<true>(L, G);
	v_cmp_gt_i32_e32 vcc, 0, v24
	v_not_b32_e32 v50, v24
	v_or_b32_e32 v24, 0x80000000, v24
	v_cndmask_b32_e32 v24, v24, v50, vcc
	v_cmp_gt_i32_e32 vcc, 0, v25
	v_not_b32_e32 v50, v25
	v_or_b32_e32 v25, 0x80000000, v25
	v_cndmask_b32_e32 v25, v25, v50, vcc
	v_cmp_gt_i32_e32 vcc, 0, v27
	v_not_b32_e32 v51, v27
	v_or_b32_e32 v27, 0x80000000, v27
	v_cndmask_b32_e32 v27, v27, v51, vcc
	v_cmp_gt_i32_e32 vcc, 0, v26
	v_not_b32_e32 v51, v26
	v_or_b32_e32 v26, 0x80000000, v26
	v_cndmask_b32_e32 v26, v26, v51, vcc
	v_and_or_b32 v24, v24, s38, v122
	v_and_or_b32 v25, v25, s38, v123
	v_and_or_b32 v27, v27, s38, v124
	v_and_or_b32 v26, v26, s38, v125
	v_max_u32_e32 v50, v24, v25
	v_min_u32_e32 v51, v27, v26
	v_min_u32_e32 v24, v24, v25
	v_max_u32_e32 v25, v27, v26
	v_min_u32_e32 v52, v50, v51
	v_min_u32_e32 v26, v24, v25
	v_max_u32_e32 v47, v50, v51
	v_max_u32_e32 v24, v24, v25
	v_max3_u32 v13, v21, v49, v40
	v_max_u32_e32 v49, v45, v48
	v_min_u32_e32 v27, v52, v26
	v_max_u32_e32 v46, v43, v44
	v_min_u32_e32 v25, v47, v24
	v_min_u32_e32 v45, v45, v48
	v_max_u32_e32 v26, v52, v26
	v_min_u32_e32 v43, v43, v44
	v_max_u32_e32 v24, v47, v24
	v_max_u32_e32 v39, v34, v38
	v_max_u32_e32 v35, v29, v32
	v_max_u32_e32 v37, v30, v33
	v_max_u32_e32 v40, v28, v31
	v_min_u32_e32 v53, v49, v27
	v_min_u32_e32 v50, v46, v25
	v_min_u32_e32 v48, v45, v26
	v_min_u32_e32 v44, v43, v24
	v_min_u32_e32 v34, v34, v38
	v_min_u32_e32 v29, v29, v32
	v_min_u32_e32 v30, v30, v33
	v_min_u32_e32 v28, v28, v31
	v_max_u32_e32 v27, v49, v27
	v_max_u32_e32 v25, v46, v25
	v_max_u32_e32 v26, v45, v26
	v_max_u32_e32 v24, v43, v24
	v_max_u32_e32 v36, v39, v35
	v_max_u32_e32 v41, v37, v40
	v_min_u32_e32 v51, v53, v50
	v_min_u32_e32 v47, v48, v44
	v_max_u32_e32 v32, v34, v29
	v_max_u32_e32 v31, v30, v28
	v_min_u32_e32 v38, v27, v25
	v_min_u32_e32 v43, v26, v24
	v_min_u32_e32 v35, v39, v35
	v_min_u32_e32 v37, v37, v40
	v_max_u32_e32 v40, v53, v50
	v_max_u32_e32 v44, v48, v44
	v_min_u32_e32 v29, v34, v29
	v_min_u32_e32 v28, v30, v28
	v_max_u32_e32 v25, v27, v25
	v_max_u32_e32 v24, v26, v24
	v_max_u32_e32 v42, v36, v41
	v_min_u32_e32 v52, v51, v47
	v_max_u32_e32 v33, v32, v31
	v_min_u32_e32 v45, v38, v43
	v_max_u32_e32 v39, v35, v37
	v_min_u32_e32 v48, v40, v44
	v_max_u32_e32 v30, v29, v28
	v_min_u32_e32 v26, v25, v24
	v_min_u32_e32 v36, v36, v41
	v_max_u32_e32 v41, v51, v47
	v_min_u32_e32 v31, v32, v31
	v_max_u32_e32 v32, v38, v43
	v_min_u32_e32 v35, v35, v37
	v_max_u32_e32 v37, v40, v44
	v_min_u32_e32 v28, v29, v28
	v_max_u32_e32 v24, v25, v24
	v_max_u32_e32 v16, v4, v6
	v_min_u32_e32 v4, v4, v6
	v_max_u32_e32 v6, v12, v14
	v_min_u32_e32 v12, v12, v14
	v_max_u32_e32 v14, v0, v2
	v_min_u32_e32 v0, v0, v2
	v_max_u32_e32 v2, v8, v10
	v_min_u32_e32 v8, v8, v10
	v_max_u32_e32 v10, v5, v7
	v_min_u32_e32 v5, v5, v7
	v_max_u32_e32 v7, v13, v15
	v_min_u32_e32 v13, v13, v15
	v_max_u32_e32 v15, v1, v3
	v_min_u32_e32 v1, v1, v3
	v_max_u32_e32 v3, v9, v11
	v_min_u32_e32 v9, v9, v11
	v_min_u32_e32 v54, v42, v52
	v_min_u32_e32 v46, v33, v45
	v_min_u32_e32 v50, v39, v48
	v_min_u32_e32 v27, v30, v26
	v_min_u32_e32 v47, v36, v41
	v_min_u32_e32 v38, v31, v32
	v_min_u32_e32 v40, v35, v37
	v_min_u32_e32 v25, v28, v24
	v_max_u32_e32 v42, v42, v52
	v_max_u32_e32 v33, v33, v45
	v_max_u32_e32 v39, v39, v48
	v_max_u32_e32 v26, v30, v26
	v_max_u32_e32 v36, v36, v41
	v_max_u32_e32 v31, v31, v32
	v_max_u32_e32 v35, v35, v37
	v_max_u32_e32 v24, v28, v24
	v_max_u32_e32 v11, v16, v10
	v_min_u32_e32 v10, v16, v10
	v_max_u32_e32 v16, v6, v7
	v_min_u32_e32 v6, v6, v7
	v_max_u32_e32 v7, v14, v15
	v_min_u32_e32 v14, v14, v15
	v_max_u32_e32 v15, v2, v3
	v_min_u32_e32 v2, v2, v3
	v_max_u32_e32 v3, v4, v5
	v_min_u32_e32 v17, v4, v5
	v_min_u32_e32 v19, v12, v13
	v_max_u32_e32 v20, v0, v1
	v_min_u32_e32 v21, v0, v1
	v_min_u32_e32 v23, v8, v9
	v_min_u32_e32 v49, v54, v46
	v_min_u32_e32 v34, v50, v27
	v_min_u32_e32 v43, v47, v38
	v_min_u32_e32 v29, v40, v25
	v_max_u32_e32 v46, v54, v46
	v_max_u32_e32 v27, v50, v27
	v_max_u32_e32 v38, v47, v38
	v_max_u32_e32 v25, v40, v25
	v_min_u32_e32 v45, v42, v33
	v_min_u32_e32 v30, v39, v26
	v_min_u32_e32 v32, v36, v31
	v_min_u32_e32 v28, v35, v24
	v_max_u32_e32 v33, v42, v33
	v_max_u32_e32 v26, v39, v26
	v_max_u32_e32 v31, v36, v31
	v_max_u32_e32 v24, v35, v24
	v_max_u32_e32 v18, v12, v13
	v_max_u32_e32 v22, v8, v9
	v_max_u32_e32 v4, v11, v7
	v_min_u32_e32 v0, v11, v7
	v_min_u32_e32 v1, v10, v14
	v_max_u32_e32 v13, v6, v2
	v_min_u32_e32 v9, v6, v2
	v_max_u32_e32 v6, v3, v20
	v_min_u32_e32 v2, v3, v20
	v_min_u32_e32 v3, v17, v21
	v_min_u32_e32 v11, v19, v23
	v_min_u32_e32 v53, v49, v34
	v_max_u32_e32 v34, v49, v34
	v_min_u32_e32 v49, v46, v27
	v_min_u32_e32 v40, v38, v25
	v_max_u32_e32 v27, v46, v27
	v_max_u32_e32 v25, v38, v25
	v_min_u32_e32 v39, v33, v26
	v_min_u32_e32 v35, v31, v24
	v_max_u32_e32 v26, v33, v26
	v_max_u32_e32 v24, v31, v24
	v_max_u32_e32 v12, v16, v15
	v_min_u32_e32 v8, v16, v15
	v_min_u32_e32 v20, v1, v9
	v_min_u32_e32 v16, v3, v11
	v_min_u32_e32 v38, v27, v25
	v_min_u32_e32 v31, v26, v24
	v_max3_u32 v1, v1, v9, v38
	v_max3_u32 v9, v20, v27, v25
	v_max3_u32 v3, v3, v11, v31
	v_max3_u32 v11, v16, v26, v24
	ds_read_b128 v[24:27], v72 offset:192
	v_max_u32_e32 v5, v10, v14
	v_min_u32_e32 v10, v18, v22
	v_min_u32_e32 v46, v45, v30
	v_min_u32_e32 v37, v32, v28
	v_max_u32_e32 v30, v45, v30
	v_max_u32_e32 v28, v32, v28
	v_max_u32_e32 v14, v18, v22
	v_min_u32_e32 v18, v2, v10
	v_min_u32_e32 v32, v30, v28
	v_min_u32_e32 v44, v43, v29
	v_max_u32_e32 v29, v43, v29
	v_max3_u32 v2, v2, v10, v32
	v_max3_u32 v10, v18, v30, v28
	s_waitcnt lgkmcnt(0)
; __device__ __forceinline__ unsigned fkey(float f) { unsigned u = __float_as_uint(f); return (u & 0x80000000u) ? ~u : (u | 0x80000000u); }
; __device__ __forceinline__ void sort16_desc(unsigned (&a)[16]) {
; #pragma unroll
;   for (int k = 2; k <= 16; k <<= 1)
; #pragma unroll
;     for (int j = k >> 1; j > 0; j >>= 1)
; #pragma unroll
;       for (int i = 0; i < 16; ++i) {
;         const int l = i ^ j;
;         if (l > i) { if ((i & k) == 0) cswap_desc(a[i], a[l]); else cswap_desc(a[l], a[i]); }
;       }
; __device__ void phase_peer_select(const Params& p, char* lds) {
;     ...
;       for (int grp = 0; grp < 4; ++grp) {
;         unsigned G[16];
; #pragma unroll
;         for (int n4 = 0; n4 < 4; ++n4) {
;           const f32x4 v = *(const f32x4*)(sp + grp * 16 + n4 * 4);
;           const unsigned ib = (unsigned)(127 - (half * 64 + grp * 16 + n4 * 4));
; #pragma unroll
;           for (int e = 0; e < 4; ++e) G[n4 * 4 + e] = (fkey(v[e]) & ~127u) | (ib - e);
;         }
;         sort16_desc(G);
;         if (grp == 0) {
; #pragma unroll
;           for (int i = 0; i < 16; ++i) L[i] = G[i];
;         } else merge16_desc<true>(L, G);
	v_cmp_gt_i32_e32 vcc, 0, v24
	v_not_b32_e32 v28, v24
	v_or_b32_e32 v24, 0x80000000, v24
	v_min_u32_e32 v22, v0, v8
	v_min_u32_e32 v43, v34, v29
	v_cndmask_b32_e32 v24, v24, v28, vcc
	v_cmp_gt_i32_e32 vcc, 0, v25
	v_not_b32_e32 v28, v25
	v_or_b32_e32 v25, 0x80000000, v25
	v_max3_u32 v0, v0, v8, v43
	v_max3_u32 v8, v22, v34, v29
	v_cndmask_b32_e32 v25, v25, v28, vcc
	v_cmp_gt_i32_e32 vcc, 0, v27
	v_not_b32_e32 v29, v27
	v_or_b32_e32 v27, 0x80000000, v27
	v_cndmask_b32_e32 v27, v27, v29, vcc
	v_cmp_gt_i32_e32 vcc, 0, v26
	v_not_b32_e32 v29, v26
	v_or_b32_e32 v26, 0x80000000, v26
	v_cndmask_b32_e32 v26, v26, v29, vcc
	v_and_or_b32 v24, v24, s38, v126
	v_and_or_b32 v25, v25, s38, v127
	v_and_or_b32 v27, v27, s38, v128
	v_and_or_b32 v26, v26, s38, v129
	v_max_u32_e32 v28, v24, v25
	v_min_u32_e32 v29, v27, v26
	v_min_u32_e32 v31, v24, v25
	v_max_u32_e32 v32, v27, v26
	ds_read_b128 v[24:27], v72 offset:208
	v_max_u32_e32 v7, v17, v21
	v_max_u32_e32 v15, v19, v23
	v_min_u32_e32 v17, v7, v15
	v_min_u32_e32 v36, v39, v35
	v_max3_u32 v7, v7, v15, v36
	v_max3_u32 v15, v17, v39, v35
	s_waitcnt lgkmcnt(0)
	v_cmp_gt_i32_e32 vcc, 0, v27
	v_not_b32_e32 v35, v27
	v_or_b32_e32 v27, 0x80000000, v27
	v_cndmask_b32_e32 v27, v27, v35, vcc
	v_cmp_gt_i32_e32 vcc, 0, v26
	v_not_b32_e32 v35, v26
	v_or_b32_e32 v26, 0x80000000, v26
	v_cndmask_b32_e32 v26, v26, v35, vcc
	v_cmp_gt_i32_e32 vcc, 0, v24
	v_not_b32_e32 v36, v24
	v_or_b32_e32 v24, 0x80000000, v24
	v_cndmask_b32_e32 v24, v24, v36, vcc
	v_cmp_gt_i32_e32 vcc, 0, v25
	v_not_b32_e32 v36, v25
	v_or_b32_e32 v25, 0x80000000, v25
	v_cndmask_b32_e32 v25, v25, v36, vcc
	v_and_or_b32 v27, v27, s38, v130
	v_and_or_b32 v26, v26, s38, v131
	v_and_or_b32 v24, v24, s38, v132
	v_and_or_b32 v25, v25, s38, v133
	v_min_u32_e32 v19, v6, v14
	v_min_u32_e32 v41, v46, v37
	v_max_u32_e32 v35, v27, v26
	v_min_u32_e32 v36, v24, v25
	v_min_u32_e32 v26, v27, v26
	v_max_u32_e32 v24, v24, v25
	v_max3_u32 v6, v6, v14, v41
	v_max3_u32 v14, v19, v46, v37
	v_max_u32_e32 v30, v28, v29
	v_max_u32_e32 v33, v31, v32
	v_min_u32_e32 v37, v35, v36
	v_min_u32_e32 v25, v26, v24
	v_min_u32_e32 v27, v28, v29
	v_min_u32_e32 v28, v31, v32
	v_max_u32_e32 v31, v35, v36
	v_max_u32_e32 v24, v26, v24
	v_max_u32_e32 v34, v30, v33
	v_min_u32_e32 v38, v37, v25
	v_max_u32_e32 v29, v27, v28
	v_min_u32_e32 v32, v31, v24
	v_min_u32_e32 v30, v30, v33
	v_max_u32_e32 v33, v37, v25
	v_min_u32_e32 v28, v27, v28
	v_max_u32_e32 v31, v31, v24
	ds_read_b128 v[24:27], v72 offset:240
	v_min_u32_e32 v23, v4, v12
	v_min_u32_e32 v51, v53, v44
	v_max3_u32 v4, v4, v12, v51
	v_max3_u32 v12, v23, v53, v44
	s_waitcnt lgkmcnt(0)
	v_cmp_gt_i32_e32 vcc, 0, v27
	v_not_b32_e32 v43, v27
	v_or_b32_e32 v27, 0x80000000, v27
	v_cndmask_b32_e32 v27, v27, v43, vcc
	v_cmp_gt_i32_e32 vcc, 0, v26
	v_not_b32_e32 v43, v26
	v_or_b32_e32 v26, 0x80000000, v26
	v_cndmask_b32_e32 v26, v26, v43, vcc
	v_cmp_gt_i32_e32 vcc, 0, v24
	v_not_b32_e32 v44, v24
	v_or_b32_e32 v24, 0x80000000, v24
	v_cndmask_b32_e32 v24, v24, v44, vcc
	v_cmp_gt_i32_e32 vcc, 0, v25
	v_not_b32_e32 v44, v25
	v_or_b32_e32 v25, 0x80000000, v25
	v_cndmask_b32_e32 v25, v25, v44, vcc
	v_min_u32_e32 v47, v49, v40
	v_and_or_b32 v27, v27, s38, v134
	v_and_or_b32 v26, v26, s38, v135
	v_and_or_b32 v24, v24, s38, v136
	v_and_or_b32 v25, v25, s38, v137
	v_min_u32_e32 v21, v5, v13
	v_max3_u32 v5, v5, v13, v47
	v_max_u32_e32 v43, v27, v26
	v_min_u32_e32 v44, v24, v25
	v_min_u32_e32 v46, v27, v26
	v_max_u32_e32 v47, v24, v25
	ds_read_b128 v[24:27], v72 offset:224
	v_max_u32_e32 v45, v43, v44
	v_max_u32_e32 v48, v46, v47
	v_min_u32_e32 v43, v43, v44
	v_min_u32_e32 v44, v46, v47
	s_waitcnt lgkmcnt(0)
	v_cmp_gt_i32_e32 vcc, 0, v24
	v_not_b32_e32 v50, v24
	v_or_b32_e32 v24, 0x80000000, v24
	v_cndmask_b32_e32 v24, v24, v50, vcc
	v_cmp_gt_i32_e32 vcc, 0, v25
	v_not_b32_e32 v50, v25
	v_or_b32_e32 v25, 0x80000000, v25
	v_cndmask_b32_e32 v25, v25, v50, vcc
	v_cmp_gt_i32_e32 vcc, 0, v27
	v_not_b32_e32 v51, v27
	v_or_b32_e32 v27, 0x80000000, v27
	v_cndmask_b32_e32 v27, v27, v51, vcc
	v_cmp_gt_i32_e32 vcc, 0, v26
	v_not_b32_e32 v51, v26
	v_or_b32_e32 v26, 0x80000000, v26
	v_cndmask_b32_e32 v26, v26, v51, vcc
	v_and_or_b32 v24, v24, s38, v138
	v_and_or_b32 v25, v25, s38, v139
	v_and_or_b32 v27, v27, s38, v140
	v_and_or_b32 v26, v26, s38, v141
	v_max_u32_e32 v50, v24, v25
	v_min_u32_e32 v51, v27, v26
	v_min_u32_e32 v24, v24, v25
	v_max_u32_e32 v25, v27, v26
	v_min_u32_e32 v52, v50, v51
	v_min_u32_e32 v26, v24, v25
	v_max_u32_e32 v47, v50, v51
	v_max_u32_e32 v24, v24, v25
	v_max3_u32 v13, v21, v49, v40
	v_max_u32_e32 v49, v45, v48
	v_min_u32_e32 v27, v52, v26
	v_max_u32_e32 v46, v43, v44
	v_min_u32_e32 v25, v47, v24
	v_min_u32_e32 v45, v45, v48
	v_max_u32_e32 v26, v52, v26
	v_min_u32_e32 v43, v43, v44
	v_max_u32_e32 v24, v47, v24
	v_max_u32_e32 v39, v34, v38
	v_max_u32_e32 v35, v29, v32
	v_max_u32_e32 v37, v30, v33
	v_max_u32_e32 v40, v28, v31
	v_min_u32_e32 v53, v49, v27
	v_min_u32_e32 v50, v46, v25
	v_min_u32_e32 v48, v45, v26
	v_min_u32_e32 v44, v43, v24
	v_min_u32_e32 v34, v34, v38
	v_min_u32_e32 v29, v29, v32
	v_min_u32_e32 v30, v30, v33
	v_min_u32_e32 v28, v28, v31
	v_max_u32_e32 v27, v49, v27
	v_max_u32_e32 v25, v46, v25
	v_max_u32_e32 v26, v45, v26
	v_max_u32_e32 v24, v43, v24
	v_max_u32_e32 v36, v39, v35
	v_max_u32_e32 v41, v37, v40
	v_min_u32_e32 v51, v53, v50
	v_min_u32_e32 v47, v48, v44
	v_max_u32_e32 v32, v34, v29
	v_max_u32_e32 v31, v30, v28
	v_min_u32_e32 v38, v27, v25
	v_min_u32_e32 v43, v26, v24
	v_min_u32_e32 v35, v39, v35
	v_min_u32_e32 v37, v37, v40
	v_max_u32_e32 v40, v53, v50
	v_max_u32_e32 v44, v48, v44
	v_min_u32_e32 v29, v34, v29
; template <bool SORT>
; __device__ __forceinline__ void merge16_desc(unsigned (&a)[16], const unsigned (&b)[16]) {
; #pragma unroll
;   for (int i = 0; i < 16; ++i) a[i] = a[i] > b[15 - i] ? a[i] : b[15 - i];
;   if (SORT) {
; #pragma unroll
;     for (int j = 8; j > 0; j >>= 1)
; #pragma unroll
;       for (int i = 0; i < 16; ++i) { const int l = i ^ j; if (l > i) cswap_desc(a[i], a[l]); }
;   }
; __device__ void phase_peer_select(const Params& p, char* lds) {
;     ...
;     __syncthreads();
;     if (half == 1) {
; #pragma unroll
;       for (int i = 0; i < 16; i += 4) { u32x4 w = {L[i], L[i + 1], L[i + 2], L[i + 3]}; *(u32x4*)(LH + (c * 64 + tok) * 20 + i) = w; }
;     }
	v_min_u32_e32 v28, v30, v28
	v_max_u32_e32 v25, v27, v25
	v_max_u32_e32 v24, v26, v24
	v_max_u32_e32 v42, v36, v41
	v_min_u32_e32 v52, v51, v47
	v_max_u32_e32 v33, v32, v31
	v_min_u32_e32 v45, v38, v43
	v_max_u32_e32 v39, v35, v37
	v_min_u32_e32 v48, v40, v44
	v_max_u32_e32 v30, v29, v28
	v_min_u32_e32 v26, v25, v24
	v_min_u32_e32 v36, v36, v41
	v_max_u32_e32 v41, v51, v47
	v_min_u32_e32 v31, v32, v31
	v_max_u32_e32 v32, v38, v43
	v_min_u32_e32 v35, v35, v37
	v_max_u32_e32 v37, v40, v44
	v_min_u32_e32 v28, v29, v28
	v_max_u32_e32 v24, v25, v24
	v_max_u32_e32 v16, v4, v6
	v_min_u32_e32 v4, v4, v6
	v_max_u32_e32 v6, v12, v14
	v_min_u32_e32 v12, v12, v14
	v_max_u32_e32 v14, v0, v2
	v_min_u32_e32 v0, v0, v2
	v_max_u32_e32 v2, v8, v10
	v_min_u32_e32 v8, v8, v10
	v_max_u32_e32 v10, v5, v7
	v_min_u32_e32 v5, v5, v7
	v_max_u32_e32 v7, v13, v15
	v_min_u32_e32 v13, v13, v15
	v_max_u32_e32 v15, v1, v3
	v_min_u32_e32 v1, v1, v3
	v_max_u32_e32 v3, v9, v11
	v_min_u32_e32 v9, v9, v11
	v_min_u32_e32 v54, v42, v52
	v_min_u32_e32 v46, v33, v45
	v_min_u32_e32 v50, v39, v48
	v_min_u32_e32 v27, v30, v26
	v_min_u32_e32 v47, v36, v41
	v_min_u32_e32 v38, v31, v32
	v_min_u32_e32 v40, v35, v37
	v_min_u32_e32 v25, v28, v24
	v_max_u32_e32 v42, v42, v52
	v_max_u32_e32 v33, v33, v45
	v_max_u32_e32 v39, v39, v48
	v_max_u32_e32 v26, v30, v26
	v_max_u32_e32 v36, v36, v41
	v_max_u32_e32 v31, v31, v32
	v_max_u32_e32 v35, v35, v37
	v_max_u32_e32 v24, v28, v24
	v_max_u32_e32 v11, v16, v10
	v_min_u32_e32 v10, v16, v10
	v_max_u32_e32 v16, v6, v7
	v_min_u32_e32 v6, v6, v7
	v_max_u32_e32 v7, v14, v15
	v_min_u32_e32 v14, v14, v15
	v_max_u32_e32 v15, v2, v3
	v_min_u32_e32 v2, v2, v3
	v_max_u32_e32 v3, v4, v5
	v_min_u32_e32 v17, v4, v5
	v_max_u32_e32 v18, v12, v13
	v_min_u32_e32 v19, v12, v13
	v_max_u32_e32 v20, v0, v1
	v_min_u32_e32 v21, v0, v1
	v_max_u32_e32 v22, v8, v9
	v_min_u32_e32 v23, v8, v9
	v_min_u32_e32 v49, v54, v46
	v_min_u32_e32 v34, v50, v27
	v_min_u32_e32 v43, v47, v38
	v_min_u32_e32 v29, v40, v25
	v_max_u32_e32 v46, v54, v46
	v_max_u32_e32 v27, v50, v27
	v_max_u32_e32 v38, v47, v38
	v_max_u32_e32 v25, v40, v25
	v_min_u32_e32 v45, v42, v33
	v_min_u32_e32 v30, v39, v26
	v_min_u32_e32 v32, v36, v31
	v_min_u32_e32 v28, v35, v24
	v_max_u32_e32 v33, v42, v33
	v_max_u32_e32 v26, v39, v26
	v_max_u32_e32 v31, v36, v31
	v_max_u32_e32 v24, v35, v24
	v_max_u32_e32 v4, v11, v7
	v_min_u32_e32 v0, v11, v7
	v_max_u32_e32 v12, v16, v15
	v_min_u32_e32 v8, v16, v15
	v_max_u32_e32 v5, v10, v14
	v_min_u32_e32 v1, v10, v14
	v_max_u32_e32 v13, v6, v2
	v_min_u32_e32 v9, v6, v2
	v_max_u32_e32 v6, v3, v20
	v_min_u32_e32 v2, v3, v20
	v_max_u32_e32 v14, v18, v22
	v_min_u32_e32 v10, v18, v22
	v_max_u32_e32 v7, v17, v21
	v_min_u32_e32 v3, v17, v21
	v_max_u32_e32 v15, v19, v23
	v_min_u32_e32 v11, v19, v23
	v_min_u32_e32 v53, v49, v34
	v_min_u32_e32 v44, v43, v29
	v_max_u32_e32 v34, v49, v34
	v_max_u32_e32 v29, v43, v29
	v_min_u32_e32 v49, v46, v27
	v_min_u32_e32 v40, v38, v25
	v_max_u32_e32 v27, v46, v27
	v_max_u32_e32 v25, v38, v25
	v_min_u32_e32 v46, v45, v30
	v_min_u32_e32 v37, v32, v28
	v_max_u32_e32 v30, v45, v30
	v_max_u32_e32 v28, v32, v28
	v_min_u32_e32 v39, v33, v26
	v_min_u32_e32 v35, v31, v24
	v_max_u32_e32 v26, v33, v26
	v_max_u32_e32 v24, v31, v24
	v_min_u32_e32 v23, v4, v12
	v_min_u32_e32 v22, v0, v8
	v_min_u32_e32 v21, v5, v13
	v_min_u32_e32 v20, v1, v9
	v_min_u32_e32 v19, v6, v14
	v_min_u32_e32 v18, v2, v10
	v_min_u32_e32 v17, v7, v15
	v_min_u32_e32 v16, v3, v11
	v_min_u32_e32 v51, v53, v44
	v_min_u32_e32 v43, v34, v29
	v_min_u32_e32 v47, v49, v40
	v_min_u32_e32 v38, v27, v25
	v_min_u32_e32 v41, v46, v37
	v_min_u32_e32 v32, v30, v28
	v_min_u32_e32 v36, v39, v35
	v_min_u32_e32 v31, v26, v24
	v_max3_u32 v4, v4, v12, v51
	v_max3_u32 v12, v23, v53, v44
	v_max3_u32 v0, v0, v8, v43
	v_max3_u32 v8, v22, v34, v29
	v_max3_u32 v5, v5, v13, v47
	v_max3_u32 v13, v21, v49, v40
	v_max3_u32 v1, v1, v9, v38
	v_max3_u32 v9, v20, v27, v25
	v_max3_u32 v6, v6, v14, v41
	v_max3_u32 v14, v19, v46, v37
	v_max3_u32 v2, v2, v10, v32
	v_max3_u32 v10, v18, v30, v28
	v_max3_u32 v7, v7, v15, v36
	v_max3_u32 v15, v17, v39, v35
	v_max3_u32 v3, v3, v11, v31
	v_max3_u32 v11, v16, v26, v24
	v_max_u32_e32 v16, v4, v6
	v_min_u32_e32 v4, v4, v6
	v_max_u32_e32 v6, v12, v14
	v_min_u32_e32 v12, v12, v14
	v_max_u32_e32 v14, v0, v2
	v_min_u32_e32 v0, v0, v2
	v_max_u32_e32 v2, v8, v10
	v_min_u32_e32 v8, v8, v10
	v_max_u32_e32 v10, v5, v7
	v_min_u32_e32 v5, v5, v7
	v_max_u32_e32 v7, v13, v15
	v_min_u32_e32 v13, v13, v15
	v_max_u32_e32 v15, v1, v3
	v_min_u32_e32 v1, v1, v3
	v_max_u32_e32 v3, v9, v11
	v_min_u32_e32 v9, v9, v11
	v_max_u32_e32 v11, v16, v10
	v_min_u32_e32 v10, v16, v10
	v_max_u32_e32 v16, v6, v7
	v_min_u32_e32 v6, v6, v7
	v_max_u32_e32 v7, v14, v15
	v_min_u32_e32 v14, v14, v15
	v_max_u32_e32 v15, v2, v3
	v_min_u32_e32 v2, v2, v3
	v_max_u32_e32 v3, v4, v5
	v_min_u32_e32 v4, v4, v5
	v_max_u32_e32 v5, v12, v13
	v_min_u32_e32 v12, v12, v13
	v_max_u32_e32 v13, v0, v1
	v_min_u32_e32 v0, v0, v1
	v_max_u32_e32 v1, v8, v9
	v_min_u32_e32 v8, v8, v9
	v_max_u32_e32 v9, v11, v7
	v_min_u32_e32 v7, v11, v7
	v_max_u32_e32 v11, v16, v15
	v_min_u32_e32 v15, v16, v15
	v_max_u32_e32 v16, v10, v14
	v_min_u32_e32 v10, v10, v14
	v_max_u32_e32 v14, v6, v2
	v_min_u32_e32 v17, v6, v2
	v_max_u32_e32 v18, v3, v13
	v_min_u32_e32 v13, v3, v13
	v_max_u32_e32 v19, v5, v1
	v_min_u32_e32 v20, v5, v1
	v_max_u32_e32 v21, v4, v0
	v_min_u32_e32 v22, v4, v0
	v_max_u32_e32 v23, v12, v8
	v_min_u32_e32 v8, v12, v8
	v_max_u32_e32 v0, v9, v11
	v_min_u32_e32 v1, v9, v11
	v_max_u32_e32 v2, v7, v15
	v_min_u32_e32 v3, v7, v15
	v_max_u32_e32 v4, v16, v14
	v_min_u32_e32 v5, v16, v14
	v_max_u32_e32 v6, v10, v17
	v_min_u32_e32 v7, v10, v17
	v_max_u32_e32 v17, v18, v19
	v_min_u32_e32 v16, v18, v19
	v_max_u32_e32 v15, v13, v20
	v_min_u32_e32 v14, v13, v20
	v_max_u32_e32 v13, v21, v23
	v_min_u32_e32 v12, v21, v23
	v_max_u32_e32 v10, v22, v8
	v_min_u32_e32 v11, v22, v8
	s_barrier
	s_and_saveexec_b64 s[0:1], s[42:43]
	s_cbranch_execz .LBB0_1096
	v_mov_b32_e32 v8, v13
	v_mov_b32_e32 v9, v12
	v_mov_b32_e32 v18, v17
	v_mov_b32_e32 v19, v16
	v_mov_b32_e32 v20, v15
	v_mov_b32_e32 v21, v14
	ds_write_b128 v73, v[0:3]
	ds_write_b128 v73, v[4:7] offset:16
	ds_write_b128 v73, v[18:21] offset:32
	ds_write_b128 v73, v[8:11] offset:48

; __device__ __forceinline__ float bflo(unsigned w) { return __uint_as_float(w << 16); }
; __device__ __forceinline__ float bfhi(unsigned w) { return __uint_as_float(w & 0xffff0000u); }
; __device__ __forceinline__ void peer_token_part(const Params& p, int t, int e_lo, int e_hi, float (&ov)[16], int lane) {
;     ...
;     u32x4 a = *(const u32x4*)(hf + (size_t)t * LDH + lane * 16), b = *(const u32x4*)(hf + (size_t)t * LDH + lane * 16 + 8);
; #pragma unroll
;     for (int i = 0; i < 4; ++i) { hv[i] = (f32v2_t){bflo(a[i]), bfhi(a[i])}; hv[4 + i] = (f32v2_t){bflo(b[i]), bfhi(b[i])}; }
; #pragma unroll
;     for (int i = 0; i < 8; ++i) o2[i] = (f32v2_t){ov[2 * i], ov[2 * i + 1]};
;   }
;   const int myi0 = seli[(size_t)t * 128 + lane], myi1 = seli[(size_t)t * 128 + 64 + lane];
;   const float mysu0 = qs[myi0], mysu1 = qs[myi1];
;   const float myw0 = selw[(size_t)t * 128 + lane] * qs[16384 + myi0], myw1 = selw[(size_t)t * 128 + 64 + lane] * qs[16384 + myi1];
.LBB0_1169:
	v_ashrrev_i32_e32 v65, 31, v64
	v_lshlrev_b64 v[0:1], 9, v[64:65]
	v_lshl_or_b32 v0, v180, 2, v0
	v_lshl_add_u64 v[2:3], s[36:37], 0, v[0:1]
	global_load_dword v66, v[2:3], off
	global_load_dword v68, v[2:3], off offset:256
	v_lshl_add_u64 v[2:3], s[18:19], 0, v[0:1]
	global_load_dword v170, v[2:3], off
	global_load_dword v171, v[2:3], off offset:256
	s_movk_i32 s2, 0x880
	v_mad_i64_i32 v[4:5], s[2:3], v64, s2, v[82:83]
	v_mov_b32_e32 v116, 0
	s_mov_b32 s52, -8
	global_load_dwordx4 v[172:175], v[4:5], off
	global_load_dwordx4 v[176:179], v[4:5], off offset:16
	v_mov_b32_e32 v117, v116
	v_mov_b32_e32 v118, v116
	v_mov_b32_e32 v119, v116
	v_mov_b32_e32 v112, v116
	v_mov_b32_e32 v113, v116
	v_mov_b32_e32 v108, v116
	v_mov_b32_e32 v109, v116
	v_mov_b32_e32 v114, v116
	v_mov_b32_e32 v115, v116
	v_mov_b32_e32 v110, v116
	v_mov_b32_e32 v111, v116
	v_mov_b32_e32 v106, v116
	v_mov_b32_e32 v107, v116
	v_mov_b32_e32 v104, v116
	v_mov_b32_e32 v105, v116
	s_waitcnt vmcnt(5)
	v_ashrrev_i32_e32 v67, 31, v66
	v_lshl_add_u64 v[8:9], v[66:67], 2, s[16:17]
	v_add_co_u32_e32 v0, vcc, s33, v8
	s_waitcnt vmcnt(4)
	v_ashrrev_i32_e32 v69, 31, v68
	v_addc_co_u32_e32 v1, vcc, 0, v9, vcc
	global_load_dword v182, v[0:1], off
	v_lshl_add_u64 v[10:11], v[68:69], 2, s[16:17]
	v_add_co_u32_e32 v0, vcc, s33, v10
	s_nop 1
	v_addc_co_u32_e32 v1, vcc, 0, v11, vcc
	global_load_dword v183, v[0:1], off
	global_load_dword v145, v[10:11], off
	global_load_dword v146, v[8:9], off
	s_waitcnt vmcnt(4)
	v_and_b32_e32 v73, 0xffff0000, v175
	v_and_b32_e32 v71, 0xffff0000, v179
	v_lshlrev_b32_e32 v70, 16, v179
	v_lshlrev_b32_e32 v72, 16, v175
	v_and_b32_e32 v75, 0xffff0000, v178
	v_lshlrev_b32_e32 v74, 16, v178
	v_and_b32_e32 v77, 0xffff0000, v174
	v_lshlrev_b32_e32 v76, 16, v174
	v_and_b32_e32 v79, 0xffff0000, v177
	v_lshlrev_b32_e32 v78, 16, v177
	v_and_b32_e32 v99, 0xffff0000, v173
	v_lshlrev_b32_e32 v98, 16, v173
	v_and_b32_e32 v101, 0xffff0000, v176
	v_lshlrev_b32_e32 v100, 16, v176
	v_and_b32_e32 v103, 0xffff0000, v172
	v_lshlrev_b32_e32 v102, 16, v172
	s_waitcnt vmcnt(2)
	v_mul_f32_e32 v67, v170, v182
	v_mul_f32_e32 v69, v171, v183
	s_branch .LBB0_1171
